# LN epilogues: counted vmcnt waits at the first consumer of each x/mod load instead of one vmcnt(0) after the first load group (waits moved to first consumer)
# speedup vs baseline: 1.0040x; 1.0040x over previous
.LBB0_239:
	s_waitcnt lgkmcnt(0)
	v_readlane_b32 s2, v254, 27
	s_mul_i32 s2, s2, 0xb4000
	v_readlane_b32 s3, v254, 28
	s_add_u32 s2, s22, s2
	s_addc_u32 s3, s23, 0
	s_add_u32 s59, s2, 0x100000
	s_addc_u32 s67, s3, 0
	s_lshr_b32 s2, s72, 14
	s_add_i32 s18, s2, 8
	s_ashr_i32 s19, s53, 4
	s_and_b64 s[2:3], s[56:57], exec
	s_cselect_b32 s2, s18, s19
	s_mul_hi_i32 s3, s2, 0x4800
	s_mulk_i32 s2, 0x4800
	s_lshl_b32 s69, s82, 8
	s_lshl_b64 s[18:19], s[2:3], 2
	v_or_b32_e32 v132, s69, v177
	s_add_u32 s2, s59, s18
	s_addc_u32 s3, s67, s19
	v_ashrrev_i32_e32 v133, 31, v132
	v_lshl_add_u64 v[132:133], v[132:133], 2, s[2:3]
	s_mov_b64 s[2:3], 0x4000
	v_or_b32_e32 v148, v179, v178
	v_lshl_add_u64 v[144:145], v[132:133], 0, s[2:3]
	s_movk_i32 s2, 0x4000
	v_add_u32_e32 v148, s69, v148
	v_add_co_u32_e32 v140, vcc, s2, v132
	v_ashrrev_i32_e32 v149, 31, v148
	v_readlane_b32 s2, v254, 48
	v_lshl_add_u64 v[152:153], v[148:149], 2, s[14:15]
	v_readlane_b32 s3, v254, 49
	v_addc_co_u32_e32 v141, vcc, 0, v133, vcc
	v_lshl_add_u64 v[154:155], v[152:153], 0, s[28:29]
	v_lshl_add_u64 v[162:163], v[152:153], 0, s[2:3]
	v_readlane_b32 s2, v254, 52
	global_load_dwordx4 v[132:135], v[144:145], off offset:64
	global_load_dwordx4 v[136:139], v[144:145], off offset:512
	s_nop 0
	global_load_dwordx4 v[140:143], v[140:141], off
	s_nop 0
	global_load_dwordx4 v[144:147], v[144:145], off offset:576
	s_nop 0
	global_load_dwordx4 v[148:151], v[154:155], off nt
	s_nop 0
	global_load_dwordx4 v[154:157], v[154:155], off offset:512 nt
	s_nop 0
	global_load_dwordx4 v[158:161], v[162:163], off nt
	global_load_dwordx4 v[170:173], v[162:163], off offset:512 nt
	v_lshl_add_u64 v[162:163], v[152:153], 0, s[36:37]
	v_readlane_b32 s3, v254, 53
	global_load_dwordx4 v[186:189], v[162:163], off nt
	global_load_dwordx4 v[190:193], v[162:163], off offset:512 nt
	v_lshl_add_u64 v[162:163], v[152:153], 0, s[2:3]
	v_readlane_b32 s2, v254, 56
	global_load_dwordx4 v[194:197], v[162:163], off nt
	global_load_dwordx4 v[198:201], v[162:163], off offset:512 nt
	v_lshl_add_u64 v[162:163], v[152:153], 0, s[42:43]
	v_readlane_b32 s3, v254, 57
	global_load_dwordx4 v[202:205], v[162:163], off nt
	global_load_dwordx4 v[214:217], v[162:163], off offset:512 nt
	v_lshl_add_u64 v[162:163], v[152:153], 0, s[2:3]
	v_readlane_b32 s2, v254, 60
	global_load_dwordx4 v[218:221], v[162:163], off nt
	global_load_dwordx4 v[222:225], v[162:163], off offset:512 nt
	v_lshl_add_u64 v[162:163], v[152:153], 0, s[48:49]
	v_readlane_b32 s3, v254, 61
	global_load_dwordx4 v[226:229], v[162:163], off nt
	global_load_dwordx4 v[230:233], v[162:163], off offset:512 nt
	v_lshl_add_u64 v[162:163], v[152:153], 0, s[2:3]
	global_load_dwordx4 v[234:237], v[162:163], off nt
	global_load_dwordx4 v[238:241], v[162:163], off offset:512 nt
	s_waitcnt vmcnt(15)
	ds_write_b128 v176, v[148:151]
	s_waitcnt vmcnt(13)
	ds_write_b128 v176, v[158:161] offset:1152
	ds_read_b128 v[148:151], v175
	ds_read_b128 v[158:161], v175 offset:64
	ds_write_b128 v176, v[154:157]
	s_waitcnt vmcnt(12)
	ds_write_b128 v176, v[170:173] offset:1152
	ds_read_b128 v[154:157], v175
	ds_read_b128 v[170:173], v175 offset:64
	v_pk_add_f32 v[142:143], v[142:143], 1.0 op_sel_hi:[1,0]
	v_pk_add_f32 v[162:163], v[140:141], 1.0 op_sel_hi:[1,0]
	s_waitcnt vmcnt(11)
	ds_write_b128 v176, v[186:189]
	s_waitcnt vmcnt(9)
	ds_write_b128 v176, v[194:197] offset:1152
	v_pk_mul_f32 v[140:141], v[142:143], 0.5 op_sel_hi:[1,0]
	v_pk_mul_f32 v[142:143], v[162:163], 0.5 op_sel_hi:[1,0]
	s_waitcnt lgkmcnt(6)
	v_pk_mul_f32 v[162:163], v[160:161], s[80:81] op_sel_hi:[1,0]
	v_pk_mul_f32 v[206:207], v[158:159], s[80:81] op_sel_hi:[1,0]
	ds_read_b128 v[158:161], v175
	ds_read_b128 v[186:189], v175 offset:64
	v_pk_mul_f32 v[150:151], v[150:151], s[80:81] op_sel_hi:[1,0]
	v_pk_mul_f32 v[148:149], v[148:149], s[80:81] op_sel_hi:[1,0]
	v_pk_add_f32 v[134:135], v[134:135], 1.0 op_sel_hi:[1,0]
	v_pk_add_f32 v[132:133], v[132:133], 1.0 op_sel_hi:[1,0]
	v_pk_fma_f32 v[130:131], v[130:131], v[140:141], v[150:151]
	v_pk_fma_f32 v[128:129], v[128:129], v[142:143], v[148:149]
	v_pk_mul_f32 v[148:149], v[134:135], 0.5 op_sel_hi:[1,0]
	v_pk_mul_f32 v[150:151], v[132:133], 0.5 op_sel_hi:[1,0]
	v_pk_fma_f32 v[134:135], v[126:127], v[148:149], v[162:163]
	v_pk_fma_f32 v[132:133], v[124:125], v[150:151], v[206:207]
	v_pk_add_f32 v[124:125], v[138:139], 1.0 op_sel_hi:[1,0]
	v_pk_add_f32 v[126:127], v[136:137], 1.0 op_sel_hi:[1,0]
	s_waitcnt lgkmcnt(5)
	v_pk_mul_f32 v[156:157], v[156:157], s[80:81] op_sel_hi:[1,0]
	v_pk_mul_f32 v[154:155], v[154:155], s[80:81] op_sel_hi:[1,0]
	v_pk_mul_f32 v[124:125], v[124:125], 0.5 op_sel_hi:[1,0]
	v_pk_mul_f32 v[126:127], v[126:127], 0.5 op_sel_hi:[1,0]
	ds_write_b128 v176, v[190:193]
	s_waitcnt vmcnt(8)
	ds_write_b128 v176, v[198:201] offset:1152
	v_pk_fma_f32 v[138:139], v[122:123], v[124:125], v[156:157]
	v_pk_fma_f32 v[136:137], v[120:121], v[126:127], v[154:155]
	s_waitcnt lgkmcnt(6)
	v_pk_mul_f32 v[162:163], v[172:173], s[80:81] op_sel_hi:[1,0]
	v_pk_mul_f32 v[194:195], v[170:171], s[80:81] op_sel_hi:[1,0]
	ds_read_b128 v[154:157], v175
	ds_read_b128 v[170:173], v175 offset:64
	v_pk_add_f32 v[120:121], v[146:147], 1.0 op_sel_hi:[1,0]
	v_pk_add_f32 v[122:123], v[144:145], 1.0 op_sel_hi:[1,0]
	v_pk_mul_f32 v[120:121], v[120:121], 0.5 op_sel_hi:[1,0]
	v_pk_mul_f32 v[122:123], v[122:123], 0.5 op_sel_hi:[1,0]
	v_pk_fma_f32 v[146:147], v[106:107], v[120:121], v[162:163]
	v_pk_fma_f32 v[144:145], v[104:105], v[122:123], v[194:195]
	s_waitcnt lgkmcnt(5)
	v_pk_mul_f32 v[104:105], v[160:161], s[80:81] op_sel_hi:[1,0]
	v_pk_mul_f32 v[106:107], v[158:159], s[80:81] op_sel_hi:[1,0]
	v_pk_fma_f32 v[110:111], v[110:111], v[140:141], v[104:105]
	v_pk_fma_f32 v[108:109], v[108:109], v[142:143], v[106:107]
	s_waitcnt lgkmcnt(4)
	v_pk_mul_f32 v[104:105], v[188:189], s[80:81] op_sel_hi:[1,0]
	v_pk_mul_f32 v[106:107], v[186:187], s[80:81] op_sel_hi:[1,0]
	v_pk_fma_f32 v[118:119], v[118:119], v[148:149], v[104:105]
	v_pk_fma_f32 v[116:117], v[116:117], v[150:151], v[106:107]
	s_waitcnt lgkmcnt(1)
	v_pk_mul_f32 v[104:105], v[156:157], s[80:81] op_sel_hi:[1,0]
	v_pk_mul_f32 v[106:107], v[154:155], s[80:81] op_sel_hi:[1,0]
	v_pk_fma_f32 v[102:103], v[102:103], v[124:125], v[104:105]
	s_waitcnt lgkmcnt(0)
	v_pk_mul_f32 v[104:105], v[172:173], s[80:81] op_sel_hi:[1,0]
	v_pk_mul_f32 v[154:155], v[170:171], s[80:81] op_sel_hi:[1,0]
	v_pk_fma_f32 v[100:101], v[100:101], v[126:127], v[106:107]
	v_pk_fma_f32 v[106:107], v[98:99], v[120:121], v[104:105]
	v_pk_fma_f32 v[104:105], v[96:97], v[122:123], v[154:155]
	v_readlane_b32 s2, v255, 0
	v_lshl_add_u64 v[96:97], v[152:153], 0, s[54:55]
	v_readlane_b32 s3, v255, 1
	global_load_dwordx4 v[154:157], v[96:97], off nt
	global_load_dwordx4 v[158:161], v[96:97], off offset:512 nt
	v_lshl_add_u64 v[96:97], v[152:153], 0, s[2:3]
	v_readlane_b32 s2, v255, 2
	global_load_dwordx4 v[170:173], v[96:97], off nt
	global_load_dwordx4 v[186:189], v[96:97], off offset:512 nt
	v_lshl_add_u64 v[96:97], v[152:153], 0, s[60:61]
	v_readlane_b32 s3, v255, 3
	global_load_dwordx4 v[190:193], v[96:97], off nt
	global_load_dwordx4 v[194:197], v[96:97], off offset:512 nt
	v_lshl_add_u64 v[96:97], v[152:153], 0, s[2:3]
	global_load_dwordx4 v[198:201], v[96:97], off nt
	global_load_dwordx4 v[250:253], v[96:97], off offset:512 nt
	s_waitcnt vmcnt(15)
	ds_write_b128 v176, v[202:205]
	s_waitcnt vmcnt(13)
	ds_write_b128 v176, v[218:221] offset:1152
	ds_read_b128 v[96:99], v175
	ds_read_b128 v[202:205], v175 offset:64
	ds_write_b128 v176, v[214:217]
	s_waitcnt vmcnt(12)
	ds_write_b128 v176, v[222:225] offset:1152
	ds_read_b128 v[214:217], v175
	ds_read_b128 v[218:221], v175 offset:64
	s_waitcnt vmcnt(11)
	ds_write_b128 v176, v[226:229]
	s_waitcnt vmcnt(9)
	ds_write_b128 v176, v[234:237] offset:1152
	ds_read_b128 v[222:225], v175
	ds_read_b128 v[226:229], v175 offset:64
	s_waitcnt lgkmcnt(9)
	v_pk_mul_f32 v[96:97], v[96:97], s[80:81] op_sel_hi:[1,0]
	v_pk_mul_f32 v[98:99], v[98:99], s[80:81] op_sel_hi:[1,0]
	v_pk_fma_f32 v[92:93], v[92:93], v[142:143], v[96:97]
	s_waitcnt lgkmcnt(8)
	v_pk_mul_f32 v[96:97], v[204:205], s[80:81] op_sel_hi:[1,0]
	v_pk_mul_f32 v[162:163], v[202:203], s[80:81] op_sel_hi:[1,0]
	v_pk_fma_f32 v[94:95], v[94:95], v[140:141], v[98:99]
	v_pk_fma_f32 v[98:99], v[90:91], v[148:149], v[96:97]
	v_pk_fma_f32 v[96:97], v[88:89], v[150:151], v[162:163]
	ds_write_b128 v176, v[230:233]
	s_waitcnt vmcnt(8)
	ds_write_b128 v176, v[238:241] offset:1152
	s_waitcnt lgkmcnt(7)
	v_pk_mul_f32 v[88:89], v[216:217], s[80:81] op_sel_hi:[1,0]
	v_pk_mul_f32 v[90:91], v[214:215], s[80:81] op_sel_hi:[1,0]
	ds_read_b128 v[202:205], v175
	ds_read_b128 v[214:217], v175 offset:64
	v_pk_fma_f32 v[86:87], v[86:87], v[124:125], v[88:89]
	s_waitcnt lgkmcnt(8)
	v_pk_mul_f32 v[88:89], v[220:221], s[80:81] op_sel_hi:[1,0]
	v_pk_mul_f32 v[162:163], v[218:219], s[80:81] op_sel_hi:[1,0]
	v_pk_fma_f32 v[84:85], v[84:85], v[126:127], v[90:91]
	v_pk_fma_f32 v[90:91], v[74:75], v[120:121], v[88:89]
	v_pk_fma_f32 v[88:89], v[72:73], v[122:123], v[162:163]
	s_waitcnt lgkmcnt(5)
	v_pk_mul_f32 v[72:73], v[224:225], s[80:81] op_sel_hi:[1,0]
	v_pk_mul_f32 v[74:75], v[222:223], s[80:81] op_sel_hi:[1,0]
	v_pk_fma_f32 v[78:79], v[78:79], v[140:141], v[72:73]
	v_pk_fma_f32 v[76:77], v[76:77], v[142:143], v[74:75]
	s_waitcnt lgkmcnt(4)
	v_pk_mul_f32 v[72:73], v[228:229], s[80:81] op_sel_hi:[1,0]
	v_pk_mul_f32 v[74:75], v[226:227], s[80:81] op_sel_hi:[1,0]
	v_pk_fma_f32 v[82:83], v[82:83], v[148:149], v[72:73]
	v_pk_fma_f32 v[80:81], v[80:81], v[150:151], v[74:75]
	s_waitcnt lgkmcnt(1)
	v_pk_mul_f32 v[72:73], v[204:205], s[80:81] op_sel_hi:[1,0]
	v_pk_mul_f32 v[74:75], v[202:203], s[80:81] op_sel_hi:[1,0]
	v_pk_fma_f32 v[70:71], v[70:71], v[124:125], v[72:73]
	s_waitcnt lgkmcnt(0)
	v_pk_mul_f32 v[72:73], v[216:217], s[80:81] op_sel_hi:[1,0]
	v_pk_mul_f32 v[162:163], v[214:215], s[80:81] op_sel_hi:[1,0]
	v_pk_fma_f32 v[68:69], v[68:69], v[126:127], v[74:75]
	v_pk_fma_f32 v[74:75], v[66:67], v[120:121], v[72:73]
	v_pk_fma_f32 v[72:73], v[64:65], v[122:123], v[162:163]
	v_readlane_b32 s2, v255, 4
	v_lshl_add_u64 v[64:65], v[152:153], 0, s[70:71]
	v_readlane_b32 s3, v255, 5
	global_load_dwordx4 v[202:205], v[64:65], off nt
	global_load_dwordx4 v[214:217], v[64:65], off offset:512 nt
	v_lshl_add_u64 v[64:65], v[152:153], 0, s[2:3]
	v_readlane_b32 s2, v255, 6
	global_load_dwordx4 v[218:221], v[64:65], off nt
	global_load_dwordx4 v[222:225], v[64:65], off offset:512 nt
	v_lshl_add_u64 v[64:65], v[152:153], 0, s[96:97]
	v_readlane_b32 s3, v255, 7
	global_load_dwordx4 v[226:229], v[64:65], off nt
	global_load_dwordx4 v[230:233], v[64:65], off offset:512 nt
	v_lshl_add_u64 v[64:65], v[152:153], 0, s[2:3]
	global_load_dwordx4 v[234:237], v[64:65], off nt
	global_load_dwordx4 v[238:241], v[64:65], off offset:512 nt
	s_waitcnt vmcnt(15)
	ds_write_b128 v176, v[154:157]
	s_waitcnt vmcnt(13)
	ds_write_b128 v176, v[170:173] offset:1152
	ds_read_b128 v[64:67], v175
	ds_read_b128 v[152:155], v175 offset:64
	ds_write_b128 v176, v[158:161]
	s_waitcnt vmcnt(12)
	ds_write_b128 v176, v[186:189] offset:1152
	ds_read_b128 v[156:159], v175
	ds_read_b128 v[160:163], v175 offset:64
	s_waitcnt vmcnt(11)
	ds_write_b128 v176, v[190:193]
	s_waitcnt vmcnt(9)
	ds_write_b128 v176, v[198:201] offset:1152
	ds_read_b128 v[170:173], v175
	ds_read_b128 v[186:189], v175 offset:64
	s_waitcnt lgkmcnt(9)
	v_pk_mul_f32 v[64:65], v[64:65], s[80:81] op_sel_hi:[1,0]
	v_pk_mul_f32 v[66:67], v[66:67], s[80:81] op_sel_hi:[1,0]
	v_pk_fma_f32 v[60:61], v[60:61], v[142:143], v[64:65]
	s_waitcnt lgkmcnt(8)
	v_pk_mul_f32 v[64:65], v[154:155], s[80:81] op_sel_hi:[1,0]
	v_pk_mul_f32 v[152:153], v[152:153], s[80:81] op_sel_hi:[1,0]
	v_pk_fma_f32 v[62:63], v[62:63], v[140:141], v[66:67]
	v_pk_fma_f32 v[66:67], v[58:59], v[148:149], v[64:65]
	v_pk_fma_f32 v[64:65], v[56:57], v[150:151], v[152:153]
	ds_write_b128 v176, v[194:197]
	s_waitcnt vmcnt(8)
	ds_write_b128 v176, v[250:253] offset:1152
	s_waitcnt lgkmcnt(7)
	v_pk_mul_f32 v[56:57], v[158:159], s[80:81] op_sel_hi:[1,0]
	v_pk_mul_f32 v[58:59], v[156:157], s[80:81] op_sel_hi:[1,0]
	ds_read_b128 v[152:155], v175
	ds_read_b128 v[156:159], v175 offset:64
	v_pk_fma_f32 v[54:55], v[54:55], v[124:125], v[56:57]
	s_waitcnt lgkmcnt(8)
	v_pk_mul_f32 v[56:57], v[162:163], s[80:81] op_sel_hi:[1,0]
	v_pk_mul_f32 v[160:161], v[160:161], s[80:81] op_sel_hi:[1,0]
	v_pk_fma_f32 v[52:53], v[52:53], v[126:127], v[58:59]
	v_pk_fma_f32 v[58:59], v[42:43], v[120:121], v[56:57]
	v_pk_fma_f32 v[56:57], v[40:41], v[122:123], v[160:161]
	s_waitcnt lgkmcnt(5)
	v_pk_mul_f32 v[40:41], v[172:173], s[80:81] op_sel_hi:[1,0]
	v_pk_mul_f32 v[42:43], v[170:171], s[80:81] op_sel_hi:[1,0]
	v_pk_fma_f32 v[46:47], v[46:47], v[140:141], v[40:41]
	v_pk_fma_f32 v[44:45], v[44:45], v[142:143], v[42:43]
	s_waitcnt lgkmcnt(4)
	v_pk_mul_f32 v[40:41], v[188:189], s[80:81] op_sel_hi:[1,0]
	v_pk_mul_f32 v[42:43], v[186:187], s[80:81] op_sel_hi:[1,0]
	v_pk_fma_f32 v[50:51], v[50:51], v[148:149], v[40:41]
	v_pk_fma_f32 v[48:49], v[48:49], v[150:151], v[42:43]
	s_waitcnt lgkmcnt(1)
	v_pk_mul_f32 v[40:41], v[154:155], s[80:81] op_sel_hi:[1,0]
	v_pk_mul_f32 v[42:43], v[152:153], s[80:81] op_sel_hi:[1,0]
	v_pk_fma_f32 v[38:39], v[38:39], v[124:125], v[40:41]
	s_waitcnt lgkmcnt(0)
	v_pk_mul_f32 v[40:41], v[158:159], s[80:81] op_sel_hi:[1,0]
	v_pk_mul_f32 v[152:153], v[156:157], s[80:81] op_sel_hi:[1,0]
	v_pk_fma_f32 v[36:37], v[36:37], v[126:127], v[42:43]
	v_pk_fma_f32 v[42:43], v[34:35], v[120:121], v[40:41]
	v_pk_fma_f32 v[40:41], v[32:33], v[122:123], v[152:153]
	s_nop 0
	s_waitcnt vmcnt(7)
	ds_write_b128 v176, v[202:205]
	s_waitcnt vmcnt(5)
	ds_write_b128 v176, v[218:221] offset:1152
	ds_read_b128 v[32:35], v175
	ds_read_b128 v[152:155], v175 offset:64
	ds_write_b128 v176, v[214:217]
	s_waitcnt vmcnt(4)
	ds_write_b128 v176, v[222:225] offset:1152
	ds_read_b128 v[156:159], v175
	ds_read_b128 v[160:163], v175 offset:64
	s_waitcnt vmcnt(3)
	ds_write_b128 v176, v[226:229]
	s_waitcnt vmcnt(1)
	ds_write_b128 v176, v[234:237] offset:1152
	ds_read_b128 v[170:173], v175
	ds_read_b128 v[186:189], v175 offset:64
	s_waitcnt lgkmcnt(9)
	v_pk_mul_f32 v[32:33], v[32:33], s[80:81] op_sel_hi:[1,0]
	v_pk_mul_f32 v[34:35], v[34:35], s[80:81] op_sel_hi:[1,0]
	v_pk_fma_f32 v[28:29], v[28:29], v[142:143], v[32:33]
	s_waitcnt lgkmcnt(8)
	v_pk_mul_f32 v[32:33], v[154:155], s[80:81] op_sel_hi:[1,0]
	v_pk_mul_f32 v[152:153], v[152:153], s[80:81] op_sel_hi:[1,0]
	v_pk_fma_f32 v[30:31], v[30:31], v[140:141], v[34:35]
	v_pk_fma_f32 v[34:35], v[26:27], v[148:149], v[32:33]
	v_pk_fma_f32 v[32:33], v[24:25], v[150:151], v[152:153]
	ds_write_b128 v176, v[230:233]
	s_waitcnt vmcnt(0)
	ds_write_b128 v176, v[238:241] offset:1152
	s_waitcnt lgkmcnt(7)
	v_pk_mul_f32 v[24:25], v[158:159], s[80:81] op_sel_hi:[1,0]
	v_pk_mul_f32 v[26:27], v[156:157], s[80:81] op_sel_hi:[1,0]
	ds_read_b128 v[152:155], v175
	ds_read_b128 v[156:159], v175 offset:64
	v_pk_fma_f32 v[22:23], v[22:23], v[124:125], v[24:25]
	s_waitcnt lgkmcnt(8)
	v_pk_mul_f32 v[24:25], v[162:163], s[80:81] op_sel_hi:[1,0]
	v_pk_mul_f32 v[160:161], v[160:161], s[80:81] op_sel_hi:[1,0]
	v_pk_fma_f32 v[20:21], v[20:21], v[126:127], v[26:27]
	v_pk_fma_f32 v[26:27], v[14:15], v[120:121], v[24:25]
	v_pk_fma_f32 v[24:25], v[12:13], v[122:123], v[160:161]
	s_waitcnt lgkmcnt(5)
	v_pk_mul_f32 v[12:13], v[172:173], s[80:81] op_sel_hi:[1,0]
	v_pk_mul_f32 v[160:161], v[170:171], s[80:81] op_sel_hi:[1,0]
	v_pk_fma_f32 v[14:15], v[114:115], v[140:141], v[12:13]
	v_pk_fma_f32 v[12:13], v[112:113], v[142:143], v[160:161]
	s_waitcnt lgkmcnt(4)
	v_pk_mul_f32 v[112:113], v[188:189], s[80:81] op_sel_hi:[1,0]
	v_pk_mul_f32 v[114:115], v[186:187], s[80:81] op_sel_hi:[1,0]
	v_pk_fma_f32 v[18:19], v[18:19], v[148:149], v[112:113]
	v_pk_fma_f32 v[16:17], v[16:17], v[150:151], v[114:115]
	s_waitcnt lgkmcnt(1)
	v_pk_mul_f32 v[112:113], v[154:155], s[80:81] op_sel_hi:[1,0]
	v_pk_mul_f32 v[114:115], v[152:153], s[80:81] op_sel_hi:[1,0]
	v_pk_fma_f32 v[6:7], v[6:7], v[124:125], v[112:113]
	s_waitcnt lgkmcnt(0)
	v_pk_mul_f32 v[112:113], v[158:159], s[80:81] op_sel_hi:[1,0]
	v_pk_fma_f32 v[4:5], v[4:5], v[126:127], v[114:115]
	v_pk_mul_f32 v[114:115], v[156:157], s[80:81] op_sel_hi:[1,0]
	v_pk_fma_f32 v[10:11], v[10:11], v[120:121], v[112:113]
	v_add_f32_e32 v112, v128, v129
	v_add_f32_e32 v113, v130, v131
	v_pk_fma_f32 v[8:9], v[8:9], v[122:123], v[114:115]
	v_add_f32_e32 v112, v112, v113
	v_mul_f32_e32 v113, v129, v129
	v_mul_f32_e32 v114, v131, v131
	v_fmac_f32_e32 v113, v128, v128
	v_fmac_f32_e32 v114, v130, v130
	v_add_f32_e32 v113, v113, v114
	v_add_f32_e32 v114, v132, v133
	v_add_f32_e32 v115, v134, v135
	v_add_f32_e32 v112, 0, v112
	v_add_f32_e32 v114, v114, v115
	v_add_f32_e32 v112, v114, v112
	v_mul_f32_e32 v114, v133, v133
	v_mul_f32_e32 v115, v135, v135
	v_fmac_f32_e32 v114, v132, v132
	v_fmac_f32_e32 v115, v134, v134
	v_add_f32_e32 v114, v114, v115
	v_add_f32_e32 v113, v113, v114
	v_add_f32_e32 v114, v136, v137
	v_add_f32_e32 v115, v138, v139
	v_add_f32_e32 v114, v114, v115
	v_add_f32_e32 v112, v114, v112
	v_mul_f32_e32 v114, v137, v137
	v_mul_f32_e32 v115, v139, v139
	v_fmac_f32_e32 v114, v136, v136
	v_fmac_f32_e32 v115, v138, v138
	v_add_f32_e32 v114, v114, v115
	v_add_f32_e32 v113, v114, v113
	v_add_f32_e32 v114, v144, v145
	v_add_f32_e32 v115, v146, v147
	v_add_f32_e32 v114, v114, v115
	v_add_f32_e32 v112, v114, v112
	v_mul_f32_e32 v114, v145, v145
	v_mul_f32_e32 v115, v147, v147
	v_fmac_f32_e32 v114, v144, v144
	v_fmac_f32_e32 v115, v146, v146
	v_add_f32_e32 v114, v114, v115
	v_add_f32_e32 v113, v114, v113
	v_mov_b32_e32 v114, v112
	v_mov_b32_e32 v115, v113
	s_nop 0
	v_permlane16_swap_b32_e32 v112, v114
	v_permlane16_swap_b32_e32 v113, v115
	v_add_f32_e32 v112, v112, v114
	v_add_f32_e32 v113, v113, v115
	v_mov_b32_e32 v114, v112
	v_mov_b32_e32 v115, v113
	s_nop 0
	v_permlane32_swap_b32_e32 v112, v114
	v_permlane32_swap_b32_e32 v113, v115
	s_and_saveexec_b64 s[2:3], s[8:9]
	v_pk_add_f32 v[112:113], v[112:113], v[114:115]
	ds_write_b64 v184, v[112:113]
	s_or_b64 exec, exec, s[2:3]
	v_add_f32_e32 v112, v108, v109
	v_add_f32_e32 v113, v110, v111
	v_add_f32_e32 v112, v112, v113
	v_mul_f32_e32 v113, v109, v109
	v_mul_f32_e32 v114, v111, v111
	v_fmac_f32_e32 v113, v108, v108
	v_fmac_f32_e32 v114, v110, v110
	v_add_f32_e32 v113, v113, v114
	v_add_f32_e32 v114, v116, v117
	v_add_f32_e32 v115, v118, v119
	v_add_f32_e32 v112, 0, v112
	v_add_f32_e32 v114, v114, v115
	v_add_f32_e32 v112, v114, v112
	v_mul_f32_e32 v114, v117, v117
	v_mul_f32_e32 v115, v119, v119
	v_fmac_f32_e32 v114, v116, v116
	v_fmac_f32_e32 v115, v118, v118
	v_add_f32_e32 v114, v114, v115
	v_add_f32_e32 v113, v113, v114
	v_add_f32_e32 v114, v100, v101
	v_add_f32_e32 v115, v102, v103
	v_add_f32_e32 v114, v114, v115
	v_add_f32_e32 v112, v114, v112
	v_mul_f32_e32 v114, v101, v101
	v_mul_f32_e32 v115, v103, v103
	v_fmac_f32_e32 v114, v100, v100
	v_fmac_f32_e32 v115, v102, v102
	v_add_f32_e32 v114, v114, v115
	v_add_f32_e32 v113, v114, v113
	v_add_f32_e32 v114, v104, v105
	v_add_f32_e32 v115, v106, v107
	v_add_f32_e32 v114, v114, v115
	v_add_f32_e32 v112, v114, v112
	v_mul_f32_e32 v114, v105, v105
	v_mul_f32_e32 v115, v107, v107
	v_fmac_f32_e32 v114, v104, v104
	v_fmac_f32_e32 v115, v106, v106
	v_add_f32_e32 v114, v114, v115
	v_add_f32_e32 v113, v114, v113
	v_mov_b32_e32 v114, v112
	v_mov_b32_e32 v115, v113
	s_nop 0
	v_permlane16_swap_b32_e32 v112, v114
	v_permlane16_swap_b32_e32 v113, v115
	v_add_f32_e32 v112, v112, v114
	v_add_f32_e32 v113, v113, v115
	v_mov_b32_e32 v114, v112
	v_mov_b32_e32 v115, v113
	s_nop 0
	v_permlane32_swap_b32_e32 v112, v114
	v_permlane32_swap_b32_e32 v113, v115
	s_and_saveexec_b64 s[2:3], s[8:9]
	v_pk_add_f32 v[112:113], v[112:113], v[114:115]
	ds_write_b64 v184, v[112:113] offset:512
	s_or_b64 exec, exec, s[2:3]
	v_add_f32_e32 v112, v92, v93
	v_add_f32_e32 v113, v94, v95
	v_add_f32_e32 v112, v112, v113
	v_mul_f32_e32 v113, v93, v93
	v_mul_f32_e32 v114, v95, v95
	v_fmac_f32_e32 v113, v92, v92
	v_fmac_f32_e32 v114, v94, v94
	v_add_f32_e32 v113, v113, v114
	v_add_f32_e32 v114, v96, v97
	v_add_f32_e32 v115, v98, v99
	v_add_f32_e32 v112, 0, v112
	v_add_f32_e32 v114, v114, v115
	v_add_f32_e32 v112, v114, v112
	v_mul_f32_e32 v114, v97, v97
	v_mul_f32_e32 v115, v99, v99
	v_fmac_f32_e32 v114, v96, v96
	v_fmac_f32_e32 v115, v98, v98
	v_add_f32_e32 v114, v114, v115
	v_add_f32_e32 v113, v113, v114
	v_add_f32_e32 v114, v84, v85
	v_add_f32_e32 v115, v86, v87
	v_add_f32_e32 v114, v114, v115
	v_add_f32_e32 v112, v114, v112
	v_mul_f32_e32 v114, v85, v85
	v_mul_f32_e32 v115, v87, v87
	v_fmac_f32_e32 v114, v84, v84
	v_fmac_f32_e32 v115, v86, v86
	v_add_f32_e32 v114, v114, v115
	v_add_f32_e32 v113, v114, v113
	v_add_f32_e32 v114, v88, v89
	v_add_f32_e32 v115, v90, v91
	v_add_f32_e32 v114, v114, v115
	v_add_f32_e32 v112, v114, v112
	v_mul_f32_e32 v114, v89, v89
	v_mul_f32_e32 v115, v91, v91
	v_fmac_f32_e32 v114, v88, v88
	v_fmac_f32_e32 v115, v90, v90
	v_add_f32_e32 v114, v114, v115
	v_add_f32_e32 v113, v114, v113
	v_mov_b32_e32 v114, v112
	v_mov_b32_e32 v115, v113
	s_nop 0
	v_permlane16_swap_b32_e32 v112, v114
	v_permlane16_swap_b32_e32 v113, v115
	v_add_f32_e32 v112, v112, v114
	v_add_f32_e32 v113, v113, v115
	v_mov_b32_e32 v114, v112
	v_mov_b32_e32 v115, v113
	s_nop 0
	v_permlane32_swap_b32_e32 v112, v114
	v_permlane32_swap_b32_e32 v113, v115
	s_and_saveexec_b64 s[2:3], s[8:9]
	v_pk_add_f32 v[112:113], v[112:113], v[114:115]
	ds_write_b64 v184, v[112:113] offset:1024
	s_or_b64 exec, exec, s[2:3]
	v_add_f32_e32 v112, v76, v77
	v_add_f32_e32 v113, v78, v79
	v_add_f32_e32 v112, v112, v113
	v_mul_f32_e32 v113, v77, v77
	v_mul_f32_e32 v114, v79, v79
	v_fmac_f32_e32 v113, v76, v76
	v_fmac_f32_e32 v114, v78, v78
	v_add_f32_e32 v113, v113, v114
	v_add_f32_e32 v114, v80, v81
	v_add_f32_e32 v115, v82, v83
	v_add_f32_e32 v112, 0, v112
	v_add_f32_e32 v114, v114, v115
	v_add_f32_e32 v112, v114, v112
	v_mul_f32_e32 v114, v81, v81
	v_mul_f32_e32 v115, v83, v83
	v_fmac_f32_e32 v114, v80, v80
	v_fmac_f32_e32 v115, v82, v82
	v_add_f32_e32 v114, v114, v115
	v_add_f32_e32 v113, v113, v114
	v_add_f32_e32 v114, v68, v69
	v_add_f32_e32 v115, v70, v71
	v_add_f32_e32 v114, v114, v115
	v_add_f32_e32 v112, v114, v112
	v_mul_f32_e32 v114, v69, v69
	v_mul_f32_e32 v115, v71, v71
	v_fmac_f32_e32 v114, v68, v68
	v_fmac_f32_e32 v115, v70, v70
	v_add_f32_e32 v114, v114, v115
	v_add_f32_e32 v113, v114, v113
	v_add_f32_e32 v114, v72, v73
	v_add_f32_e32 v115, v74, v75
	v_add_f32_e32 v114, v114, v115
	v_add_f32_e32 v112, v114, v112
	v_mul_f32_e32 v114, v73, v73
	v_mul_f32_e32 v115, v75, v75
	v_fmac_f32_e32 v114, v72, v72
	v_fmac_f32_e32 v115, v74, v74
	v_add_f32_e32 v114, v114, v115
	v_add_f32_e32 v113, v114, v113
	v_mov_b32_e32 v114, v112
	v_mov_b32_e32 v115, v113
	s_nop 0
	v_permlane16_swap_b32_e32 v112, v114
	v_permlane16_swap_b32_e32 v113, v115
	v_add_f32_e32 v112, v112, v114
	v_add_f32_e32 v113, v113, v115
	v_mov_b32_e32 v114, v112
	v_mov_b32_e32 v115, v113
	s_nop 0
	v_permlane32_swap_b32_e32 v112, v114
	v_permlane32_swap_b32_e32 v113, v115
	s_and_saveexec_b64 s[2:3], s[8:9]
	v_pk_add_f32 v[112:113], v[112:113], v[114:115]
	ds_write_b64 v184, v[112:113] offset:1536
	s_or_b64 exec, exec, s[2:3]
	v_add_f32_e32 v112, v60, v61
	v_add_f32_e32 v113, v62, v63
	v_add_f32_e32 v112, v112, v113
	v_mul_f32_e32 v113, v61, v61
	v_mul_f32_e32 v114, v63, v63
	v_fmac_f32_e32 v113, v60, v60
	v_fmac_f32_e32 v114, v62, v62
	v_add_f32_e32 v113, v113, v114
	v_add_f32_e32 v114, v64, v65
	v_add_f32_e32 v115, v66, v67
	v_add_f32_e32 v112, 0, v112
	v_add_f32_e32 v114, v114, v115
	v_add_f32_e32 v112, v114, v112
	v_mul_f32_e32 v114, v65, v65
	v_mul_f32_e32 v115, v67, v67
	v_fmac_f32_e32 v114, v64, v64
	v_fmac_f32_e32 v115, v66, v66
	v_add_f32_e32 v114, v114, v115
	v_add_f32_e32 v113, v113, v114
	v_add_f32_e32 v114, v52, v53
	v_add_f32_e32 v115, v54, v55
	v_add_f32_e32 v114, v114, v115
	v_add_f32_e32 v112, v114, v112
	v_mul_f32_e32 v114, v53, v53
	v_mul_f32_e32 v115, v55, v55
	v_fmac_f32_e32 v114, v52, v52
	v_fmac_f32_e32 v115, v54, v54
	v_add_f32_e32 v114, v114, v115
	v_add_f32_e32 v113, v114, v113
	v_add_f32_e32 v114, v56, v57
	v_add_f32_e32 v115, v58, v59
	v_add_f32_e32 v114, v114, v115
	v_add_f32_e32 v112, v114, v112
	v_mul_f32_e32 v114, v57, v57
	v_mul_f32_e32 v115, v59, v59
	v_fmac_f32_e32 v114, v56, v56
	v_fmac_f32_e32 v115, v58, v58
	v_add_f32_e32 v114, v114, v115
	v_add_f32_e32 v113, v114, v113
	v_mov_b32_e32 v114, v112
	v_mov_b32_e32 v115, v113
	s_nop 0
	v_permlane16_swap_b32_e32 v112, v114
	v_permlane16_swap_b32_e32 v113, v115
	v_add_f32_e32 v112, v112, v114
	v_add_f32_e32 v113, v113, v115
	v_mov_b32_e32 v114, v112
	v_mov_b32_e32 v115, v113
	s_nop 0
	v_permlane32_swap_b32_e32 v112, v114
	v_permlane32_swap_b32_e32 v113, v115
	s_and_saveexec_b64 s[2:3], s[8:9]
	v_pk_add_f32 v[112:113], v[112:113], v[114:115]
	ds_write_b64 v184, v[112:113] offset:4096
	s_or_b64 exec, exec, s[2:3]
	v_add_f32_e32 v112, v44, v45
	v_add_f32_e32 v113, v46, v47
	v_add_f32_e32 v112, v112, v113
	v_mul_f32_e32 v113, v45, v45
	v_mul_f32_e32 v114, v47, v47
	v_fmac_f32_e32 v113, v44, v44
	v_fmac_f32_e32 v114, v46, v46
	v_add_f32_e32 v113, v113, v114
	v_add_f32_e32 v114, v48, v49
	v_add_f32_e32 v115, v50, v51
	v_add_f32_e32 v112, 0, v112
	v_add_f32_e32 v114, v114, v115
	v_add_f32_e32 v112, v114, v112
	v_mul_f32_e32 v114, v49, v49
	v_mul_f32_e32 v115, v51, v51
	v_fmac_f32_e32 v114, v48, v48
	v_fmac_f32_e32 v115, v50, v50
	v_add_f32_e32 v114, v114, v115
	v_add_f32_e32 v113, v113, v114
	v_add_f32_e32 v114, v36, v37
	v_add_f32_e32 v115, v38, v39
	v_add_f32_e32 v114, v114, v115
	v_add_f32_e32 v112, v114, v112
	v_mul_f32_e32 v114, v37, v37
	v_mul_f32_e32 v115, v39, v39
	v_fmac_f32_e32 v114, v36, v36
	v_fmac_f32_e32 v115, v38, v38
	v_add_f32_e32 v114, v114, v115
	v_add_f32_e32 v113, v114, v113
	v_add_f32_e32 v114, v40, v41
	v_add_f32_e32 v115, v42, v43
	v_add_f32_e32 v114, v114, v115
	v_add_f32_e32 v112, v114, v112
	v_mul_f32_e32 v114, v41, v41
	v_mul_f32_e32 v115, v43, v43
	v_fmac_f32_e32 v114, v40, v40
	v_fmac_f32_e32 v115, v42, v42
	v_add_f32_e32 v114, v114, v115
	v_add_f32_e32 v113, v114, v113
	v_mov_b32_e32 v114, v112
	v_mov_b32_e32 v115, v113
	s_nop 0
	v_permlane16_swap_b32_e32 v112, v114
	v_permlane16_swap_b32_e32 v113, v115
	v_add_f32_e32 v112, v112, v114
	v_add_f32_e32 v113, v113, v115
	v_mov_b32_e32 v114, v112
	v_mov_b32_e32 v115, v113
	s_nop 0
	v_permlane32_swap_b32_e32 v112, v114
	v_permlane32_swap_b32_e32 v113, v115
	s_and_saveexec_b64 s[2:3], s[8:9]
	v_pk_add_f32 v[112:113], v[112:113], v[114:115]
	ds_write_b64 v184, v[112:113] offset:4608
	s_or_b64 exec, exec, s[2:3]
	v_add_f32_e32 v112, v28, v29
	v_add_f32_e32 v113, v30, v31
	v_add_f32_e32 v112, v112, v113
	v_mul_f32_e32 v113, v29, v29
	v_mul_f32_e32 v114, v31, v31
	v_fmac_f32_e32 v113, v28, v28
	v_fmac_f32_e32 v114, v30, v30
	v_add_f32_e32 v113, v113, v114
	v_add_f32_e32 v114, v32, v33
	v_add_f32_e32 v115, v34, v35
	v_add_f32_e32 v112, 0, v112
	v_add_f32_e32 v114, v114, v115
	v_add_f32_e32 v112, v114, v112
	v_mul_f32_e32 v114, v33, v33
	v_mul_f32_e32 v115, v35, v35
	v_fmac_f32_e32 v114, v32, v32
	v_fmac_f32_e32 v115, v34, v34
	v_add_f32_e32 v114, v114, v115
	v_add_f32_e32 v113, v113, v114
	v_add_f32_e32 v114, v20, v21
	v_add_f32_e32 v115, v22, v23
	v_add_f32_e32 v114, v114, v115
	v_add_f32_e32 v112, v114, v112
	v_mul_f32_e32 v114, v21, v21
	v_mul_f32_e32 v115, v23, v23
	v_fmac_f32_e32 v114, v20, v20
	v_fmac_f32_e32 v115, v22, v22
	v_add_f32_e32 v114, v114, v115
	v_add_f32_e32 v113, v114, v113
	v_add_f32_e32 v114, v24, v25
	v_add_f32_e32 v115, v26, v27
	v_add_f32_e32 v114, v114, v115
	v_add_f32_e32 v112, v114, v112
	v_mul_f32_e32 v114, v25, v25
	v_mul_f32_e32 v115, v27, v27
	v_fmac_f32_e32 v114, v24, v24
	v_fmac_f32_e32 v115, v26, v26
	v_add_f32_e32 v114, v114, v115
	v_add_f32_e32 v113, v114, v113
	v_mov_b32_e32 v114, v112
	v_mov_b32_e32 v115, v113
	s_nop 0
	v_permlane16_swap_b32_e32 v112, v114
	v_permlane16_swap_b32_e32 v113, v115
	v_add_f32_e32 v112, v112, v114
	v_add_f32_e32 v113, v113, v115
	v_mov_b32_e32 v114, v112
	v_mov_b32_e32 v115, v113
	s_nop 0
	v_permlane32_swap_b32_e32 v112, v114
	v_permlane32_swap_b32_e32 v113, v115
	s_and_saveexec_b64 s[2:3], s[8:9]
	v_pk_add_f32 v[112:113], v[112:113], v[114:115]
	ds_write_b64 v184, v[112:113] offset:5120
	s_or_b64 exec, exec, s[2:3]
	v_add_f32_e32 v112, v12, v13
	v_add_f32_e32 v113, v14, v15
	v_add_f32_e32 v112, v112, v113
	v_mul_f32_e32 v113, v13, v13
	v_mul_f32_e32 v114, v15, v15
	v_fmac_f32_e32 v113, v12, v12
	v_fmac_f32_e32 v114, v14, v14
	v_add_f32_e32 v113, v113, v114
	v_add_f32_e32 v114, v16, v17
	v_add_f32_e32 v115, v18, v19
	v_add_f32_e32 v112, 0, v112
	v_add_f32_e32 v114, v114, v115
	v_add_f32_e32 v112, v114, v112
	v_mul_f32_e32 v114, v17, v17
	v_mul_f32_e32 v115, v19, v19
	v_fmac_f32_e32 v114, v16, v16
	v_fmac_f32_e32 v115, v18, v18
	v_add_f32_e32 v114, v114, v115
	v_add_f32_e32 v113, v113, v114
	v_add_f32_e32 v114, v4, v5
	v_add_f32_e32 v115, v6, v7
	v_add_f32_e32 v114, v114, v115
	v_add_f32_e32 v112, v114, v112
	v_mul_f32_e32 v114, v5, v5
	v_mul_f32_e32 v115, v7, v7
	v_fmac_f32_e32 v114, v4, v4
	v_fmac_f32_e32 v115, v6, v6
	v_add_f32_e32 v114, v114, v115
	v_add_f32_e32 v113, v114, v113
	v_add_f32_e32 v114, v8, v9
	v_add_f32_e32 v115, v10, v11
	v_add_f32_e32 v114, v114, v115
	v_add_f32_e32 v112, v114, v112
	v_mul_f32_e32 v114, v9, v9
	v_mul_f32_e32 v115, v11, v11
	v_fmac_f32_e32 v114, v8, v8
	v_fmac_f32_e32 v115, v10, v10
	v_add_f32_e32 v114, v114, v115
	v_add_f32_e32 v113, v114, v113
	v_mov_b32_e32 v114, v112
	v_mov_b32_e32 v115, v113
	s_nop 0
	v_permlane16_swap_b32_e32 v112, v114
	v_permlane16_swap_b32_e32 v113, v115
	v_add_f32_e32 v112, v112, v114
	v_add_f32_e32 v113, v113, v115
	v_mov_b32_e32 v114, v112
	v_mov_b32_e32 v115, v113
	s_nop 0
	v_permlane32_swap_b32_e32 v112, v114
	v_permlane32_swap_b32_e32 v113, v115
	s_and_saveexec_b64 s[2:3], s[8:9]
	v_pk_add_f32 v[112:113], v[112:113], v[114:115]
	ds_write_b64 v184, v[112:113] offset:5632
	s_or_b64 exec, exec, s[2:3]
	s_waitcnt lgkmcnt(0)
	s_barrier
	s_add_u32 s14, s22, 0xac00000
	v_add_u32_e32 v170, s66, v180
	s_addc_u32 s15, s23, 0
	v_ashrrev_i32_e32 v171, 31, v170
	s_and_saveexec_b64 s[2:3], s[10:11]
	s_cbranch_execz .LBB0_257
	ds_read_b128 v[112:115], v183
	ds_read_b128 v[120:123], v183 offset:16
	s_ashr_i32 s83, s82, 31
	s_waitcnt lgkmcnt(1)
	v_mov_b32_e32 v124, v112
	s_waitcnt lgkmcnt(0)
	v_mov_b32_e32 v125, v120
	v_mov_b32_e32 v126, v114
	v_mov_b32_e32 v127, v122
	v_pk_add_f32 v[124:125], v[124:125], v[126:127]
	v_mov_b32_e32 v120, v113
	v_mov_b32_e32 v122, v115
	v_add_f32_e32 v114, v124, v125
	v_pk_add_f32 v[112:113], v[120:121], v[122:123]
	s_nop 0
	v_add_f32_e32 v113, v112, v113
	v_mul_f32_e32 v112, 0x3b800000, v114
	v_fma_f32 v113, -v114, v112, v113
	v_lshlrev_b64 v[114:115], 6, v[170:171]
	v_lshl_add_u64 v[114:115], s[14:15], 0, v[114:115]
	v_max_f32_e32 v113, 0, v113
	v_lshl_add_u64 v[114:115], s[82:83], 3, v[114:115]
	global_store_dwordx2 v[114:115], v[112:113], off sc1

.LBB0_647:
	v_readlane_b32 s5, v254, 35
	s_waitcnt lgkmcnt(0)
	s_add_u32 s5, s22, s5
	s_addc_u32 s19, s23, 0
	s_add_u32 s5, s5, 0x100000
	s_addc_u32 s49, s19, 0
	s_lshr_b32 s19, s72, 14
	s_add_i32 s19, s19, 8
	s_ashr_i32 s29, s18, 4
	s_and_b64 s[54:55], s[54:55], exec
	s_cselect_b32 s19, s19, s29
	s_lshl_b32 s29, s28, 8
	s_mul_hi_i32 s55, s19, 0x4800
	s_mul_i32 s54, s19, 0x4800
	s_or_b32 s63, s29, s51
	s_lshl_b64 s[54:55], s[54:55], 2
	v_or_b32_e32 v132, s63, v179
	s_add_u32 s66, s5, s54
	s_addc_u32 s67, s49, s55
	v_ashrrev_i32_e32 v133, 31, v132
	v_lshl_add_u64 v[132:133], v[132:133], 2, s[66:67]
	s_mov_b32 s19, 0xa000
	s_mov_b64 s[66:67], 0xa000
	v_add_co_u32_e32 v142, vcc, s19, v132
	v_lshl_add_u64 v[140:141], v[132:133], 0, s[66:67]
	s_nop 0
	v_addc_co_u32_e32 v143, vcc, 0, v133, vcc
	global_load_dwordx4 v[132:135], v[140:141], off offset:64
	global_load_dwordx4 v[136:139], v[140:141], off offset:512
	s_nop 0
	global_load_dwordx4 v[142:145], v[142:143], off
	s_nop 0
	global_load_dwordx4 v[154:157], v[140:141], off offset:576
	v_or3_b32 v140, v183, s51, v181
	v_add_u32_e32 v140, s29, v140
	v_ashrrev_i32_e32 v141, 31, v140
	v_lshl_add_u64 v[152:153], v[140:141], 2, s[60:61]
	v_readlane_b32 s60, v254, 54
	v_lshl_add_u64 v[140:141], v[152:153], 0, s[6:7]
	v_readlane_b32 s61, v254, 55
	global_load_dwordx4 v[146:149], v[140:141], off nt
	global_load_dwordx4 v[158:161], v[140:141], off offset:512 nt
	v_lshl_add_u64 v[140:141], v[152:153], 0, s[60:61]
	v_readlane_b32 s60, v254, 58
	global_load_dwordx4 v[174:177], v[140:141], off nt
	global_load_dwordx4 v[190:193], v[140:141], off offset:512 nt
	v_lshl_add_u64 v[140:141], v[152:153], 0, s[34:35]
	v_readlane_b32 s61, v254, 59
	global_load_dwordx4 v[194:197], v[140:141], off nt
	global_load_dwordx4 v[198:201], v[140:141], off offset:512 nt
	v_lshl_add_u64 v[140:141], v[152:153], 0, s[60:61]
	v_readlane_b32 s60, v254, 62
	global_load_dwordx4 v[202:205], v[140:141], off nt
	global_load_dwordx4 v[214:217], v[140:141], off offset:512 nt
	v_lshl_add_u64 v[140:141], v[152:153], 0, s[40:41]
	v_readlane_b32 s61, v254, 63
	global_load_dwordx4 v[218:221], v[140:141], off nt
	global_load_dwordx4 v[222:225], v[140:141], off offset:512 nt
	v_lshl_add_u64 v[140:141], v[152:153], 0, s[60:61]
	v_readlane_b32 s60, v255, 2
	global_load_dwordx4 v[226:229], v[140:141], off nt
	global_load_dwordx4 v[230:233], v[140:141], off offset:512 nt
	v_lshl_add_u64 v[140:141], v[152:153], 0, s[46:47]
	v_readlane_b32 s61, v255, 3
	global_load_dwordx4 v[234:237], v[140:141], off nt
	global_load_dwordx4 v[238:241], v[140:141], off offset:512 nt
	v_lshl_add_u64 v[140:141], v[152:153], 0, s[60:61]
	global_load_dwordx4 v[250:253], v[140:141], off nt
	global_load_dwordx4 v[206:209], v[140:141], off offset:512 nt
	s_waitcnt vmcnt(15)
	ds_write_b128 v182, v[146:149]
	s_waitcnt vmcnt(13)
	ds_write_b128 v182, v[174:177] offset:1152
	ds_read_b128 v[146:149], v180
	ds_read_b128 v[174:177], v180 offset:64
	ds_write_b128 v182, v[158:161]
	s_waitcnt vmcnt(12)
	ds_write_b128 v182, v[190:193] offset:1152
	ds_read_b128 v[158:161], v180
	ds_read_b128 v[190:193], v180 offset:64
	s_waitcnt lgkmcnt(5)
	v_pk_mul_f32 v[146:147], v[146:147], s[80:81] op_sel_hi:[1,0]
	v_pk_add_f32 v[142:143], v[142:143], 1.0 op_sel_hi:[1,0]
	s_waitcnt vmcnt(11)
	ds_write_b128 v182, v[194:197]
	s_waitcnt vmcnt(9)
	ds_write_b128 v182, v[202:205] offset:1152
	v_pk_add_f32 v[140:141], v[144:145], 1.0 op_sel_hi:[1,0]
	v_pk_fma_f32 v[128:129], v[128:129], v[142:143], v[146:147]
	s_waitcnt lgkmcnt(6)
	v_pk_mul_f32 v[144:145], v[176:177], s[80:81] op_sel_hi:[1,0]
	v_pk_mul_f32 v[146:147], v[174:175], s[80:81] op_sel_hi:[1,0]
	ds_read_b128 v[174:177], v180
	ds_read_b128 v[194:197], v180 offset:64
	v_pk_mul_f32 v[148:149], v[148:149], s[80:81] op_sel_hi:[1,0]
	v_pk_add_f32 v[150:151], v[132:133], 1.0 op_sel_hi:[1,0]
	v_pk_fma_f32 v[130:131], v[130:131], v[140:141], v[148:149]
	v_pk_add_f32 v[148:149], v[134:135], 1.0 op_sel_hi:[1,0]
	v_pk_fma_f32 v[132:133], v[124:125], v[150:151], v[146:147]
	v_pk_fma_f32 v[134:135], v[126:127], v[148:149], v[144:145]
	s_waitcnt lgkmcnt(5)
	v_pk_mul_f32 v[144:145], v[160:161], s[80:81] op_sel_hi:[1,0]
	v_pk_add_f32 v[124:125], v[138:139], 1.0 op_sel_hi:[1,0]
	ds_write_b128 v182, v[198:201]
	s_waitcnt vmcnt(8)
	ds_write_b128 v182, v[214:217] offset:1152
	v_pk_mul_f32 v[146:147], v[158:159], s[80:81] op_sel_hi:[1,0]
	v_pk_fma_f32 v[138:139], v[122:123], v[124:125], v[144:145]
	s_waitcnt lgkmcnt(6)
	v_pk_mul_f32 v[144:145], v[192:193], s[80:81] op_sel_hi:[1,0]
	v_pk_mul_f32 v[162:163], v[190:191], s[80:81] op_sel_hi:[1,0]
	ds_read_b128 v[158:161], v180
	ds_read_b128 v[190:193], v180 offset:64
	v_pk_add_f32 v[126:127], v[136:137], 1.0 op_sel_hi:[1,0]
	v_pk_add_f32 v[122:123], v[154:155], 1.0 op_sel_hi:[1,0]
	v_pk_fma_f32 v[136:137], v[120:121], v[126:127], v[146:147]
	v_pk_add_f32 v[120:121], v[156:157], 1.0 op_sel_hi:[1,0]
	s_nop 0
	v_pk_fma_f32 v[146:147], v[106:107], v[120:121], v[144:145]
	v_pk_fma_f32 v[144:145], v[104:105], v[122:123], v[162:163]
	s_waitcnt lgkmcnt(5)
	v_pk_mul_f32 v[104:105], v[176:177], s[80:81] op_sel_hi:[1,0]
	v_pk_mul_f32 v[106:107], v[174:175], s[80:81] op_sel_hi:[1,0]
	v_pk_fma_f32 v[110:111], v[110:111], v[140:141], v[104:105]
	v_pk_fma_f32 v[108:109], v[108:109], v[142:143], v[106:107]
	s_waitcnt lgkmcnt(4)
	v_pk_mul_f32 v[104:105], v[196:197], s[80:81] op_sel_hi:[1,0]
	v_pk_mul_f32 v[106:107], v[194:195], s[80:81] op_sel_hi:[1,0]
	v_pk_fma_f32 v[118:119], v[118:119], v[148:149], v[104:105]
	v_pk_fma_f32 v[116:117], v[116:117], v[150:151], v[106:107]
	s_waitcnt lgkmcnt(1)
	v_pk_mul_f32 v[104:105], v[160:161], s[80:81] op_sel_hi:[1,0]
	v_pk_mul_f32 v[106:107], v[158:159], s[80:81] op_sel_hi:[1,0]
	v_pk_fma_f32 v[102:103], v[102:103], v[124:125], v[104:105]
	s_waitcnt lgkmcnt(0)
	v_pk_mul_f32 v[104:105], v[192:193], s[80:81] op_sel_hi:[1,0]
	v_pk_mul_f32 v[154:155], v[190:191], s[80:81] op_sel_hi:[1,0]
	v_pk_fma_f32 v[100:101], v[100:101], v[126:127], v[106:107]
	v_pk_fma_f32 v[106:107], v[98:99], v[120:121], v[104:105]
	v_pk_fma_f32 v[104:105], v[96:97], v[122:123], v[154:155]
	v_readlane_b32 s60, v255, 6
	v_lshl_add_u64 v[96:97], v[152:153], 0, s[52:53]
	v_readlane_b32 s61, v255, 7
	global_load_dwordx4 v[154:157], v[96:97], off nt
	global_load_dwordx4 v[158:161], v[96:97], off offset:512 nt
	v_lshl_add_u64 v[96:97], v[152:153], 0, s[60:61]
	v_readlane_b32 s60, v255, 12
	global_load_dwordx4 v[174:177], v[96:97], off nt
	global_load_dwordx4 v[190:193], v[96:97], off offset:512 nt
	v_lshl_add_u64 v[96:97], v[152:153], 0, s[58:59]
	v_readlane_b32 s61, v255, 13
	global_load_dwordx4 v[194:197], v[96:97], off nt
	global_load_dwordx4 v[198:201], v[96:97], off offset:512 nt
	v_lshl_add_u64 v[96:97], v[152:153], 0, s[60:61]
	global_load_dwordx4 v[202:205], v[96:97], off nt
	global_load_dwordx4 v[214:217], v[96:97], off offset:512 nt
	s_waitcnt vmcnt(15)
	ds_write_b128 v182, v[218:221]
	s_waitcnt vmcnt(13)
	ds_write_b128 v182, v[226:229] offset:1152
	ds_read_b128 v[96:99], v180
	ds_read_b128 v[218:221], v180 offset:64
	ds_write_b128 v182, v[222:225]
	s_waitcnt vmcnt(12)
	ds_write_b128 v182, v[230:233] offset:1152
	ds_read_b128 v[222:225], v180
	ds_read_b128 v[226:229], v180 offset:64
	s_waitcnt vmcnt(11)
	ds_write_b128 v182, v[234:237]
	s_waitcnt vmcnt(9)
	ds_write_b128 v182, v[250:253] offset:1152
	ds_read_b128 v[230:233], v180
	ds_read_b128 v[234:237], v180 offset:64
	s_waitcnt lgkmcnt(9)
	v_pk_mul_f32 v[96:97], v[96:97], s[80:81] op_sel_hi:[1,0]
	v_pk_mul_f32 v[98:99], v[98:99], s[80:81] op_sel_hi:[1,0]
	v_pk_fma_f32 v[92:93], v[92:93], v[142:143], v[96:97]
	s_waitcnt lgkmcnt(8)
	v_pk_mul_f32 v[96:97], v[220:221], s[80:81] op_sel_hi:[1,0]
	v_pk_mul_f32 v[162:163], v[218:219], s[80:81] op_sel_hi:[1,0]
	v_pk_fma_f32 v[94:95], v[94:95], v[140:141], v[98:99]
	v_pk_fma_f32 v[98:99], v[90:91], v[148:149], v[96:97]
	v_pk_fma_f32 v[96:97], v[88:89], v[150:151], v[162:163]
	ds_write_b128 v182, v[238:241]
	s_waitcnt vmcnt(8)
	ds_write_b128 v182, v[206:209] offset:1152
	ds_read_b128 v[206:209], v180
	ds_read_b128 v[218:221], v180 offset:64
	s_waitcnt lgkmcnt(9)
	v_pk_mul_f32 v[88:89], v[224:225], s[80:81] op_sel_hi:[1,0]
	v_pk_mul_f32 v[90:91], v[222:223], s[80:81] op_sel_hi:[1,0]
	v_pk_fma_f32 v[86:87], v[86:87], v[124:125], v[88:89]
	s_waitcnt lgkmcnt(8)
	v_pk_mul_f32 v[88:89], v[228:229], s[80:81] op_sel_hi:[1,0]
	v_pk_mul_f32 v[162:163], v[226:227], s[80:81] op_sel_hi:[1,0]
	v_pk_fma_f32 v[84:85], v[84:85], v[126:127], v[90:91]
	v_pk_fma_f32 v[90:91], v[74:75], v[120:121], v[88:89]
	v_pk_fma_f32 v[88:89], v[72:73], v[122:123], v[162:163]
	s_waitcnt lgkmcnt(5)
	v_pk_mul_f32 v[72:73], v[232:233], s[80:81] op_sel_hi:[1,0]
	v_pk_mul_f32 v[74:75], v[230:231], s[80:81] op_sel_hi:[1,0]
	v_pk_fma_f32 v[78:79], v[78:79], v[140:141], v[72:73]
	v_pk_fma_f32 v[76:77], v[76:77], v[142:143], v[74:75]
	s_waitcnt lgkmcnt(4)
	v_pk_mul_f32 v[72:73], v[236:237], s[80:81] op_sel_hi:[1,0]
	v_pk_mul_f32 v[74:75], v[234:235], s[80:81] op_sel_hi:[1,0]
	v_pk_fma_f32 v[82:83], v[82:83], v[148:149], v[72:73]
	v_pk_fma_f32 v[80:81], v[80:81], v[150:151], v[74:75]
	s_waitcnt lgkmcnt(1)
	v_pk_mul_f32 v[72:73], v[208:209], s[80:81] op_sel_hi:[1,0]
	v_pk_mul_f32 v[74:75], v[206:207], s[80:81] op_sel_hi:[1,0]
	v_pk_fma_f32 v[70:71], v[70:71], v[124:125], v[72:73]
	s_waitcnt lgkmcnt(0)
	v_pk_mul_f32 v[72:73], v[220:221], s[80:81] op_sel_hi:[1,0]
	v_pk_mul_f32 v[162:163], v[218:219], s[80:81] op_sel_hi:[1,0]
	v_pk_fma_f32 v[68:69], v[68:69], v[126:127], v[74:75]
	v_pk_fma_f32 v[74:75], v[66:67], v[120:121], v[72:73]
	v_pk_fma_f32 v[72:73], v[64:65], v[122:123], v[162:163]
	v_readlane_b32 s60, v254, 40
	v_lshl_add_u64 v[64:65], v[152:153], 0, s[64:65]
	v_readlane_b32 s61, v254, 41
	global_load_dwordx4 v[206:209], v[64:65], off nt
	global_load_dwordx4 v[218:221], v[64:65], off offset:512 nt
	v_lshl_add_u64 v[64:65], v[152:153], 0, s[60:61]
	v_readlane_b32 s60, v254, 42
	global_load_dwordx4 v[222:225], v[64:65], off nt
	global_load_dwordx4 v[226:229], v[64:65], off offset:512 nt
	v_lshl_add_u64 v[64:65], v[152:153], 0, s[78:79]
	v_readlane_b32 s61, v254, 43
	global_load_dwordx4 v[230:233], v[64:65], off nt
	global_load_dwordx4 v[234:237], v[64:65], off offset:512 nt
	v_lshl_add_u64 v[64:65], v[152:153], 0, s[60:61]
	global_load_dwordx4 v[238:241], v[64:65], off nt
	global_load_dwordx4 v[250:253], v[64:65], off offset:512 nt
	s_waitcnt vmcnt(15)
	ds_write_b128 v182, v[154:157]
	s_waitcnt vmcnt(13)
	ds_write_b128 v182, v[174:177] offset:1152
	ds_read_b128 v[64:67], v180
	ds_read_b128 v[152:155], v180 offset:64
	ds_write_b128 v182, v[158:161]
	s_waitcnt vmcnt(12)
	ds_write_b128 v182, v[190:193] offset:1152
	ds_read_b128 v[156:159], v180
	ds_read_b128 v[160:163], v180 offset:64
	s_waitcnt vmcnt(11)
	ds_write_b128 v182, v[194:197]
	s_waitcnt vmcnt(9)
	ds_write_b128 v182, v[202:205] offset:1152
	ds_read_b128 v[174:177], v180
	ds_read_b128 v[190:193], v180 offset:64
	s_waitcnt lgkmcnt(9)
	v_pk_mul_f32 v[64:65], v[64:65], s[80:81] op_sel_hi:[1,0]
	v_pk_mul_f32 v[66:67], v[66:67], s[80:81] op_sel_hi:[1,0]
	v_pk_fma_f32 v[60:61], v[60:61], v[142:143], v[64:65]
	s_waitcnt lgkmcnt(8)
	v_pk_mul_f32 v[64:65], v[154:155], s[80:81] op_sel_hi:[1,0]
	v_pk_mul_f32 v[152:153], v[152:153], s[80:81] op_sel_hi:[1,0]
	v_pk_fma_f32 v[62:63], v[62:63], v[140:141], v[66:67]
	v_pk_fma_f32 v[66:67], v[58:59], v[148:149], v[64:65]
	v_pk_fma_f32 v[64:65], v[56:57], v[150:151], v[152:153]
	ds_write_b128 v182, v[198:201]
	s_waitcnt vmcnt(8)
	ds_write_b128 v182, v[214:217] offset:1152
	s_waitcnt lgkmcnt(7)
	v_pk_mul_f32 v[56:57], v[158:159], s[80:81] op_sel_hi:[1,0]
	v_pk_mul_f32 v[58:59], v[156:157], s[80:81] op_sel_hi:[1,0]
	ds_read_b128 v[152:155], v180
	ds_read_b128 v[156:159], v180 offset:64
	v_pk_fma_f32 v[54:55], v[54:55], v[124:125], v[56:57]
	s_waitcnt lgkmcnt(8)
	v_pk_mul_f32 v[56:57], v[162:163], s[80:81] op_sel_hi:[1,0]
	v_pk_mul_f32 v[160:161], v[160:161], s[80:81] op_sel_hi:[1,0]
	v_pk_fma_f32 v[52:53], v[52:53], v[126:127], v[58:59]
	v_pk_fma_f32 v[58:59], v[42:43], v[120:121], v[56:57]
	v_pk_fma_f32 v[56:57], v[40:41], v[122:123], v[160:161]
	s_waitcnt lgkmcnt(5)
	v_pk_mul_f32 v[40:41], v[176:177], s[80:81] op_sel_hi:[1,0]
	v_pk_mul_f32 v[42:43], v[174:175], s[80:81] op_sel_hi:[1,0]
	v_pk_fma_f32 v[46:47], v[46:47], v[140:141], v[40:41]
	v_pk_fma_f32 v[44:45], v[44:45], v[142:143], v[42:43]
	s_waitcnt lgkmcnt(4)
	v_pk_mul_f32 v[40:41], v[192:193], s[80:81] op_sel_hi:[1,0]
	v_pk_mul_f32 v[42:43], v[190:191], s[80:81] op_sel_hi:[1,0]
	v_pk_fma_f32 v[50:51], v[50:51], v[148:149], v[40:41]
	v_pk_fma_f32 v[48:49], v[48:49], v[150:151], v[42:43]
	s_waitcnt lgkmcnt(1)
	v_pk_mul_f32 v[40:41], v[154:155], s[80:81] op_sel_hi:[1,0]
	v_pk_mul_f32 v[42:43], v[152:153], s[80:81] op_sel_hi:[1,0]
	v_pk_fma_f32 v[38:39], v[38:39], v[124:125], v[40:41]
	s_waitcnt lgkmcnt(0)
	v_pk_mul_f32 v[40:41], v[158:159], s[80:81] op_sel_hi:[1,0]
	v_pk_mul_f32 v[152:153], v[156:157], s[80:81] op_sel_hi:[1,0]
	v_pk_fma_f32 v[36:37], v[36:37], v[126:127], v[42:43]
	v_pk_fma_f32 v[42:43], v[34:35], v[120:121], v[40:41]
	v_pk_fma_f32 v[40:41], v[32:33], v[122:123], v[152:153]
	s_nop 0
	s_waitcnt vmcnt(7)
	ds_write_b128 v182, v[206:209]
	s_waitcnt vmcnt(5)
	ds_write_b128 v182, v[222:225] offset:1152
	ds_read_b128 v[32:35], v180
	ds_read_b128 v[152:155], v180 offset:64
	ds_write_b128 v182, v[218:221]
	s_waitcnt vmcnt(4)
	ds_write_b128 v182, v[226:229] offset:1152
	ds_read_b128 v[156:159], v180
	ds_read_b128 v[160:163], v180 offset:64
	s_waitcnt vmcnt(3)
	ds_write_b128 v182, v[230:233]
	s_waitcnt vmcnt(1)
	ds_write_b128 v182, v[238:241] offset:1152
	ds_read_b128 v[174:177], v180
	ds_read_b128 v[190:193], v180 offset:64
	s_waitcnt lgkmcnt(9)
	v_pk_mul_f32 v[32:33], v[32:33], s[80:81] op_sel_hi:[1,0]
	v_pk_mul_f32 v[34:35], v[34:35], s[80:81] op_sel_hi:[1,0]
	v_pk_fma_f32 v[28:29], v[28:29], v[142:143], v[32:33]
	s_waitcnt lgkmcnt(8)
	v_pk_mul_f32 v[32:33], v[154:155], s[80:81] op_sel_hi:[1,0]
	v_pk_mul_f32 v[152:153], v[152:153], s[80:81] op_sel_hi:[1,0]
	v_pk_fma_f32 v[30:31], v[30:31], v[140:141], v[34:35]
	v_pk_fma_f32 v[34:35], v[26:27], v[148:149], v[32:33]
	v_pk_fma_f32 v[32:33], v[24:25], v[150:151], v[152:153]
	ds_write_b128 v182, v[234:237]
	s_waitcnt vmcnt(0)
	ds_write_b128 v182, v[250:253] offset:1152
	s_waitcnt lgkmcnt(7)
	v_pk_mul_f32 v[24:25], v[158:159], s[80:81] op_sel_hi:[1,0]
	v_pk_mul_f32 v[26:27], v[156:157], s[80:81] op_sel_hi:[1,0]
	ds_read_b128 v[152:155], v180
	ds_read_b128 v[156:159], v180 offset:64
	v_pk_fma_f32 v[22:23], v[22:23], v[124:125], v[24:25]
	s_waitcnt lgkmcnt(8)
	v_pk_mul_f32 v[24:25], v[162:163], s[80:81] op_sel_hi:[1,0]
	v_pk_mul_f32 v[160:161], v[160:161], s[80:81] op_sel_hi:[1,0]
	v_pk_fma_f32 v[20:21], v[20:21], v[126:127], v[26:27]
	v_pk_fma_f32 v[26:27], v[14:15], v[120:121], v[24:25]
	v_pk_fma_f32 v[24:25], v[12:13], v[122:123], v[160:161]
	s_waitcnt lgkmcnt(5)
	v_pk_mul_f32 v[12:13], v[176:177], s[80:81] op_sel_hi:[1,0]
	v_pk_mul_f32 v[160:161], v[174:175], s[80:81] op_sel_hi:[1,0]
	v_pk_fma_f32 v[14:15], v[114:115], v[140:141], v[12:13]
	v_pk_fma_f32 v[12:13], v[112:113], v[142:143], v[160:161]
	s_waitcnt lgkmcnt(4)
	v_pk_mul_f32 v[112:113], v[192:193], s[80:81] op_sel_hi:[1,0]
	v_pk_mul_f32 v[114:115], v[190:191], s[80:81] op_sel_hi:[1,0]
	v_pk_fma_f32 v[18:19], v[18:19], v[148:149], v[112:113]
	v_pk_fma_f32 v[16:17], v[16:17], v[150:151], v[114:115]
	s_waitcnt lgkmcnt(1)
	v_pk_mul_f32 v[112:113], v[154:155], s[80:81] op_sel_hi:[1,0]
	v_pk_mul_f32 v[114:115], v[152:153], s[80:81] op_sel_hi:[1,0]
	v_pk_fma_f32 v[6:7], v[6:7], v[124:125], v[112:113]
	s_waitcnt lgkmcnt(0)
	v_pk_mul_f32 v[112:113], v[158:159], s[80:81] op_sel_hi:[1,0]
	v_pk_fma_f32 v[4:5], v[4:5], v[126:127], v[114:115]
	v_pk_mul_f32 v[114:115], v[156:157], s[80:81] op_sel_hi:[1,0]
	v_pk_fma_f32 v[10:11], v[10:11], v[120:121], v[112:113]
	v_add_f32_e32 v112, v128, v129
	v_add_f32_e32 v113, v130, v131
	v_pk_fma_f32 v[8:9], v[8:9], v[122:123], v[114:115]
	v_add_f32_e32 v112, v112, v113
	v_mul_f32_e32 v113, v129, v129
	v_mul_f32_e32 v114, v131, v131
	v_fmac_f32_e32 v113, v128, v128
	v_fmac_f32_e32 v114, v130, v130
	v_add_f32_e32 v113, v113, v114
	v_add_f32_e32 v114, v132, v133
	v_add_f32_e32 v115, v134, v135
	v_add_f32_e32 v112, 0, v112
	v_add_f32_e32 v114, v114, v115
	v_add_f32_e32 v112, v114, v112
	v_mul_f32_e32 v114, v133, v133
	v_mul_f32_e32 v115, v135, v135
	v_fmac_f32_e32 v114, v132, v132
	v_fmac_f32_e32 v115, v134, v134
	v_add_f32_e32 v114, v114, v115
	v_add_f32_e32 v113, v113, v114
	v_add_f32_e32 v114, v136, v137
	v_add_f32_e32 v115, v138, v139
	v_add_f32_e32 v114, v114, v115
	v_add_f32_e32 v112, v114, v112
	v_mul_f32_e32 v114, v137, v137
	v_mul_f32_e32 v115, v139, v139
	v_fmac_f32_e32 v114, v136, v136
	v_fmac_f32_e32 v115, v138, v138
	v_add_f32_e32 v114, v114, v115
	v_add_f32_e32 v113, v114, v113
	v_add_f32_e32 v114, v144, v145
	v_add_f32_e32 v115, v146, v147
	v_add_f32_e32 v114, v114, v115
	v_add_f32_e32 v112, v114, v112
	v_mul_f32_e32 v114, v145, v145
	v_mul_f32_e32 v115, v147, v147
	v_fmac_f32_e32 v114, v144, v144
	v_fmac_f32_e32 v115, v146, v146
	v_add_f32_e32 v114, v114, v115
	v_add_f32_e32 v113, v114, v113
	v_mov_b32_e32 v114, v112
	v_mov_b32_e32 v115, v113
	s_nop 0
	v_permlane16_swap_b32_e32 v112, v114
	v_permlane16_swap_b32_e32 v113, v115
	v_add_f32_e32 v112, v112, v114
	v_add_f32_e32 v113, v113, v115
	v_mov_b32_e32 v114, v112
	v_mov_b32_e32 v115, v113
	s_nop 0
	v_permlane32_swap_b32_e32 v112, v114
	v_permlane32_swap_b32_e32 v113, v115
	s_and_saveexec_b64 s[60:61], s[8:9]
	v_pk_add_f32 v[112:113], v[112:113], v[114:115]
	ds_write_b64 v188, v[112:113]
	s_or_b64 exec, exec, s[60:61]
	v_add_f32_e32 v112, v108, v109
	v_add_f32_e32 v113, v110, v111
	v_add_f32_e32 v112, v112, v113
	v_mul_f32_e32 v113, v109, v109
	v_mul_f32_e32 v114, v111, v111
	v_fmac_f32_e32 v113, v108, v108
	v_fmac_f32_e32 v114, v110, v110
	v_add_f32_e32 v113, v113, v114
	v_add_f32_e32 v114, v116, v117
	v_add_f32_e32 v115, v118, v119
	v_add_f32_e32 v112, 0, v112
	v_add_f32_e32 v114, v114, v115
	v_add_f32_e32 v112, v114, v112
	v_mul_f32_e32 v114, v117, v117
	v_mul_f32_e32 v115, v119, v119
	v_fmac_f32_e32 v114, v116, v116
	v_fmac_f32_e32 v115, v118, v118
	v_add_f32_e32 v114, v114, v115
	v_add_f32_e32 v113, v113, v114
	v_add_f32_e32 v114, v100, v101
	v_add_f32_e32 v115, v102, v103
	v_add_f32_e32 v114, v114, v115
	v_add_f32_e32 v112, v114, v112
	v_mul_f32_e32 v114, v101, v101
	v_mul_f32_e32 v115, v103, v103
	v_fmac_f32_e32 v114, v100, v100
	v_fmac_f32_e32 v115, v102, v102
	v_add_f32_e32 v114, v114, v115
	v_add_f32_e32 v113, v114, v113
	v_add_f32_e32 v114, v104, v105
	v_add_f32_e32 v115, v106, v107
	v_add_f32_e32 v114, v114, v115
	v_add_f32_e32 v112, v114, v112
	v_mul_f32_e32 v114, v105, v105
	v_mul_f32_e32 v115, v107, v107
	v_fmac_f32_e32 v114, v104, v104
	v_fmac_f32_e32 v115, v106, v106
	v_add_f32_e32 v114, v114, v115
	v_add_f32_e32 v113, v114, v113
	v_mov_b32_e32 v114, v112
	v_mov_b32_e32 v115, v113
	s_nop 0
	v_permlane16_swap_b32_e32 v112, v114
	v_permlane16_swap_b32_e32 v113, v115
	v_add_f32_e32 v112, v112, v114
	v_add_f32_e32 v113, v113, v115
	v_mov_b32_e32 v114, v112
	v_mov_b32_e32 v115, v113
	s_nop 0
	v_permlane32_swap_b32_e32 v112, v114
	v_permlane32_swap_b32_e32 v113, v115
	s_and_saveexec_b64 s[60:61], s[8:9]
	v_pk_add_f32 v[112:113], v[112:113], v[114:115]
	ds_write_b64 v188, v[112:113] offset:512
	s_or_b64 exec, exec, s[60:61]
	v_add_f32_e32 v112, v92, v93
	v_add_f32_e32 v113, v94, v95
	v_add_f32_e32 v112, v112, v113
	v_mul_f32_e32 v113, v93, v93
	v_mul_f32_e32 v114, v95, v95
	v_fmac_f32_e32 v113, v92, v92
	v_fmac_f32_e32 v114, v94, v94
	v_add_f32_e32 v113, v113, v114
	v_add_f32_e32 v114, v96, v97
	v_add_f32_e32 v115, v98, v99
	v_add_f32_e32 v112, 0, v112
	v_add_f32_e32 v114, v114, v115
	v_add_f32_e32 v112, v114, v112
	v_mul_f32_e32 v114, v97, v97
	v_mul_f32_e32 v115, v99, v99
	v_fmac_f32_e32 v114, v96, v96
	v_fmac_f32_e32 v115, v98, v98
	v_add_f32_e32 v114, v114, v115
	v_add_f32_e32 v113, v113, v114
	v_add_f32_e32 v114, v84, v85
	v_add_f32_e32 v115, v86, v87
	v_add_f32_e32 v114, v114, v115
	v_add_f32_e32 v112, v114, v112
	v_mul_f32_e32 v114, v85, v85
	v_mul_f32_e32 v115, v87, v87
	v_fmac_f32_e32 v114, v84, v84
	v_fmac_f32_e32 v115, v86, v86
	v_add_f32_e32 v114, v114, v115
	v_add_f32_e32 v113, v114, v113
	v_add_f32_e32 v114, v88, v89
	v_add_f32_e32 v115, v90, v91
	v_add_f32_e32 v114, v114, v115
	v_add_f32_e32 v112, v114, v112
	v_mul_f32_e32 v114, v89, v89
	v_mul_f32_e32 v115, v91, v91
	v_fmac_f32_e32 v114, v88, v88
	v_fmac_f32_e32 v115, v90, v90
	v_add_f32_e32 v114, v114, v115
	v_add_f32_e32 v113, v114, v113
	v_mov_b32_e32 v114, v112
	v_mov_b32_e32 v115, v113
	s_nop 0
	v_permlane16_swap_b32_e32 v112, v114
	v_permlane16_swap_b32_e32 v113, v115
	v_add_f32_e32 v112, v112, v114
	v_add_f32_e32 v113, v113, v115
	v_mov_b32_e32 v114, v112
	v_mov_b32_e32 v115, v113
	s_nop 0
	v_permlane32_swap_b32_e32 v112, v114
	v_permlane32_swap_b32_e32 v113, v115
	s_and_saveexec_b64 s[60:61], s[8:9]
	v_pk_add_f32 v[112:113], v[112:113], v[114:115]
	ds_write_b64 v188, v[112:113] offset:1024
	s_or_b64 exec, exec, s[60:61]
	v_add_f32_e32 v112, v76, v77
	v_add_f32_e32 v113, v78, v79
	v_add_f32_e32 v112, v112, v113
	v_mul_f32_e32 v113, v77, v77
	v_mul_f32_e32 v114, v79, v79
	v_fmac_f32_e32 v113, v76, v76
	v_fmac_f32_e32 v114, v78, v78
	v_add_f32_e32 v113, v113, v114
	v_add_f32_e32 v114, v80, v81
	v_add_f32_e32 v115, v82, v83
	v_add_f32_e32 v112, 0, v112
	v_add_f32_e32 v114, v114, v115
	v_add_f32_e32 v112, v114, v112
	v_mul_f32_e32 v114, v81, v81
	v_mul_f32_e32 v115, v83, v83
	v_fmac_f32_e32 v114, v80, v80
	v_fmac_f32_e32 v115, v82, v82
	v_add_f32_e32 v114, v114, v115
	v_add_f32_e32 v113, v113, v114
	v_add_f32_e32 v114, v68, v69
	v_add_f32_e32 v115, v70, v71
	v_add_f32_e32 v114, v114, v115
	v_add_f32_e32 v112, v114, v112
	v_mul_f32_e32 v114, v69, v69
	v_mul_f32_e32 v115, v71, v71
	v_fmac_f32_e32 v114, v68, v68
	v_fmac_f32_e32 v115, v70, v70
	v_add_f32_e32 v114, v114, v115
	v_add_f32_e32 v113, v114, v113
	v_add_f32_e32 v114, v72, v73
	v_add_f32_e32 v115, v74, v75
	v_add_f32_e32 v114, v114, v115
	v_add_f32_e32 v112, v114, v112
	v_mul_f32_e32 v114, v73, v73
	v_mul_f32_e32 v115, v75, v75
	v_fmac_f32_e32 v114, v72, v72
	v_fmac_f32_e32 v115, v74, v74
	v_add_f32_e32 v114, v114, v115
	v_add_f32_e32 v113, v114, v113
	v_mov_b32_e32 v114, v112
	v_mov_b32_e32 v115, v113
	s_nop 0
	v_permlane16_swap_b32_e32 v112, v114
	v_permlane16_swap_b32_e32 v113, v115
	v_add_f32_e32 v112, v112, v114
	v_add_f32_e32 v113, v113, v115
	v_mov_b32_e32 v114, v112
	v_mov_b32_e32 v115, v113
	s_nop 0
	v_permlane32_swap_b32_e32 v112, v114
	v_permlane32_swap_b32_e32 v113, v115
	s_and_saveexec_b64 s[60:61], s[8:9]
	v_pk_add_f32 v[112:113], v[112:113], v[114:115]
	ds_write_b64 v188, v[112:113] offset:1536
	s_or_b64 exec, exec, s[60:61]
	v_add_f32_e32 v112, v60, v61
	v_add_f32_e32 v113, v62, v63
	v_add_f32_e32 v112, v112, v113
	v_mul_f32_e32 v113, v61, v61
	v_mul_f32_e32 v114, v63, v63
	v_fmac_f32_e32 v113, v60, v60
	v_fmac_f32_e32 v114, v62, v62
	v_add_f32_e32 v113, v113, v114
	v_add_f32_e32 v114, v64, v65
	v_add_f32_e32 v115, v66, v67
	v_add_f32_e32 v112, 0, v112
	v_add_f32_e32 v114, v114, v115
	v_add_f32_e32 v112, v114, v112
	v_mul_f32_e32 v114, v65, v65
	v_mul_f32_e32 v115, v67, v67
	v_fmac_f32_e32 v114, v64, v64
	v_fmac_f32_e32 v115, v66, v66
	v_add_f32_e32 v114, v114, v115
	v_add_f32_e32 v113, v113, v114
	v_add_f32_e32 v114, v52, v53
	v_add_f32_e32 v115, v54, v55
	v_add_f32_e32 v114, v114, v115
	v_add_f32_e32 v112, v114, v112
	v_mul_f32_e32 v114, v53, v53
	v_mul_f32_e32 v115, v55, v55
	v_fmac_f32_e32 v114, v52, v52
	v_fmac_f32_e32 v115, v54, v54
	v_add_f32_e32 v114, v114, v115
	v_add_f32_e32 v113, v114, v113
	v_add_f32_e32 v114, v56, v57
	v_add_f32_e32 v115, v58, v59
	v_add_f32_e32 v114, v114, v115
	v_add_f32_e32 v112, v114, v112
	v_mul_f32_e32 v114, v57, v57
	v_mul_f32_e32 v115, v59, v59
	v_fmac_f32_e32 v114, v56, v56
	v_fmac_f32_e32 v115, v58, v58
	v_add_f32_e32 v114, v114, v115
	v_add_f32_e32 v113, v114, v113
	v_mov_b32_e32 v114, v112
	v_mov_b32_e32 v115, v113
	s_nop 0
	v_permlane16_swap_b32_e32 v112, v114
	v_permlane16_swap_b32_e32 v113, v115
	v_add_f32_e32 v112, v112, v114
	v_add_f32_e32 v113, v113, v115
	v_mov_b32_e32 v114, v112
	v_mov_b32_e32 v115, v113
	s_nop 0
	v_permlane32_swap_b32_e32 v112, v114
	v_permlane32_swap_b32_e32 v113, v115
	s_and_saveexec_b64 s[60:61], s[8:9]
	v_pk_add_f32 v[112:113], v[112:113], v[114:115]
	ds_write_b64 v188, v[112:113] offset:4096
	s_or_b64 exec, exec, s[60:61]
	v_add_f32_e32 v112, v44, v45
	v_add_f32_e32 v113, v46, v47
	v_add_f32_e32 v112, v112, v113
	v_mul_f32_e32 v113, v45, v45
	v_mul_f32_e32 v114, v47, v47
	v_fmac_f32_e32 v113, v44, v44
	v_fmac_f32_e32 v114, v46, v46
	v_add_f32_e32 v113, v113, v114
	v_add_f32_e32 v114, v48, v49
	v_add_f32_e32 v115, v50, v51
	v_add_f32_e32 v112, 0, v112
	v_add_f32_e32 v114, v114, v115
	v_add_f32_e32 v112, v114, v112
	v_mul_f32_e32 v114, v49, v49
	v_mul_f32_e32 v115, v51, v51
	v_fmac_f32_e32 v114, v48, v48
	v_fmac_f32_e32 v115, v50, v50
	v_add_f32_e32 v114, v114, v115
	v_add_f32_e32 v113, v113, v114
	v_add_f32_e32 v114, v36, v37
	v_add_f32_e32 v115, v38, v39
	v_add_f32_e32 v114, v114, v115
	v_add_f32_e32 v112, v114, v112
	v_mul_f32_e32 v114, v37, v37
	v_mul_f32_e32 v115, v39, v39
	v_fmac_f32_e32 v114, v36, v36
	v_fmac_f32_e32 v115, v38, v38
	v_add_f32_e32 v114, v114, v115
	v_add_f32_e32 v113, v114, v113
	v_add_f32_e32 v114, v40, v41
	v_add_f32_e32 v115, v42, v43
	v_add_f32_e32 v114, v114, v115
	v_add_f32_e32 v112, v114, v112
	v_mul_f32_e32 v114, v41, v41
	v_mul_f32_e32 v115, v43, v43
	v_fmac_f32_e32 v114, v40, v40
	v_fmac_f32_e32 v115, v42, v42
	v_add_f32_e32 v114, v114, v115
	v_add_f32_e32 v113, v114, v113
	v_mov_b32_e32 v114, v112
	v_mov_b32_e32 v115, v113
	s_nop 0
	v_permlane16_swap_b32_e32 v112, v114
	v_permlane16_swap_b32_e32 v113, v115
	v_add_f32_e32 v112, v112, v114
	v_add_f32_e32 v113, v113, v115
	v_mov_b32_e32 v114, v112
	v_mov_b32_e32 v115, v113
	s_nop 0
	v_permlane32_swap_b32_e32 v112, v114
	v_permlane32_swap_b32_e32 v113, v115
	s_and_saveexec_b64 s[60:61], s[8:9]
	v_pk_add_f32 v[112:113], v[112:113], v[114:115]
	ds_write_b64 v188, v[112:113] offset:4608
	s_or_b64 exec, exec, s[60:61]
	v_add_f32_e32 v112, v28, v29
	v_add_f32_e32 v113, v30, v31
	v_add_f32_e32 v112, v112, v113
	v_mul_f32_e32 v113, v29, v29
	v_mul_f32_e32 v114, v31, v31
	v_fmac_f32_e32 v113, v28, v28
	v_fmac_f32_e32 v114, v30, v30
	v_add_f32_e32 v113, v113, v114
	v_add_f32_e32 v114, v32, v33
	v_add_f32_e32 v115, v34, v35
	v_add_f32_e32 v112, 0, v112
	v_add_f32_e32 v114, v114, v115
	v_add_f32_e32 v112, v114, v112
	v_mul_f32_e32 v114, v33, v33
	v_mul_f32_e32 v115, v35, v35
	v_fmac_f32_e32 v114, v32, v32
	v_fmac_f32_e32 v115, v34, v34
	v_add_f32_e32 v114, v114, v115
	v_add_f32_e32 v113, v113, v114
	v_add_f32_e32 v114, v20, v21
	v_add_f32_e32 v115, v22, v23
	v_add_f32_e32 v114, v114, v115
	v_add_f32_e32 v112, v114, v112
	v_mul_f32_e32 v114, v21, v21
	v_mul_f32_e32 v115, v23, v23
	v_fmac_f32_e32 v114, v20, v20
	v_fmac_f32_e32 v115, v22, v22
	v_add_f32_e32 v114, v114, v115
	v_add_f32_e32 v113, v114, v113
	v_add_f32_e32 v114, v24, v25
	v_add_f32_e32 v115, v26, v27
	v_add_f32_e32 v114, v114, v115
	v_add_f32_e32 v112, v114, v112
	v_mul_f32_e32 v114, v25, v25
	v_mul_f32_e32 v115, v27, v27
	v_fmac_f32_e32 v114, v24, v24
	v_fmac_f32_e32 v115, v26, v26
	v_add_f32_e32 v114, v114, v115
	v_add_f32_e32 v113, v114, v113
	v_mov_b32_e32 v114, v112
	v_mov_b32_e32 v115, v113
	s_nop 0
	v_permlane16_swap_b32_e32 v112, v114
	v_permlane16_swap_b32_e32 v113, v115
	v_add_f32_e32 v112, v112, v114
	v_add_f32_e32 v113, v113, v115
	v_mov_b32_e32 v114, v112
	v_mov_b32_e32 v115, v113
	s_nop 0
	v_permlane32_swap_b32_e32 v112, v114
	v_permlane32_swap_b32_e32 v113, v115
	s_and_saveexec_b64 s[60:61], s[8:9]
	v_pk_add_f32 v[112:113], v[112:113], v[114:115]
	ds_write_b64 v188, v[112:113] offset:5120
	s_or_b64 exec, exec, s[60:61]
	v_add_f32_e32 v112, v12, v13
	v_add_f32_e32 v113, v14, v15
	v_add_f32_e32 v112, v112, v113
	v_mul_f32_e32 v113, v13, v13
	v_mul_f32_e32 v114, v15, v15
	v_fmac_f32_e32 v113, v12, v12
	v_fmac_f32_e32 v114, v14, v14
	v_add_f32_e32 v113, v113, v114
	v_add_f32_e32 v114, v16, v17
	v_add_f32_e32 v115, v18, v19
	v_add_f32_e32 v112, 0, v112
	v_add_f32_e32 v114, v114, v115
	v_add_f32_e32 v112, v114, v112
	v_mul_f32_e32 v114, v17, v17
	v_mul_f32_e32 v115, v19, v19
	v_fmac_f32_e32 v114, v16, v16
	v_fmac_f32_e32 v115, v18, v18
	v_add_f32_e32 v114, v114, v115
	v_add_f32_e32 v113, v113, v114
	v_add_f32_e32 v114, v4, v5
	v_add_f32_e32 v115, v6, v7
	v_add_f32_e32 v114, v114, v115
	v_add_f32_e32 v112, v114, v112
	v_mul_f32_e32 v114, v5, v5
	v_mul_f32_e32 v115, v7, v7
	v_fmac_f32_e32 v114, v4, v4
	v_fmac_f32_e32 v115, v6, v6
	v_add_f32_e32 v114, v114, v115
	v_add_f32_e32 v113, v114, v113
	v_add_f32_e32 v114, v8, v9
	v_add_f32_e32 v115, v10, v11
	v_add_f32_e32 v114, v114, v115
	v_add_f32_e32 v112, v114, v112
	v_mul_f32_e32 v114, v9, v9
	v_mul_f32_e32 v115, v11, v11
	v_fmac_f32_e32 v114, v8, v8
	v_fmac_f32_e32 v115, v10, v10
	v_add_f32_e32 v114, v114, v115
	v_add_f32_e32 v113, v114, v113
	v_mov_b32_e32 v114, v112
	v_mov_b32_e32 v115, v113
	s_nop 0
	v_permlane16_swap_b32_e32 v112, v114
	v_permlane16_swap_b32_e32 v113, v115
	v_add_f32_e32 v112, v112, v114
	v_add_f32_e32 v113, v113, v115
	v_mov_b32_e32 v114, v112
	v_mov_b32_e32 v115, v113
	s_nop 0
	v_permlane32_swap_b32_e32 v112, v114
	v_permlane32_swap_b32_e32 v113, v115
	s_and_saveexec_b64 s[60:61], s[8:9]
	v_pk_add_f32 v[112:113], v[112:113], v[114:115]
	ds_write_b64 v188, v[112:113] offset:5632
	s_or_b64 exec, exec, s[60:61]
	s_waitcnt lgkmcnt(0)
	s_barrier
	s_add_u32 s60, s22, 0x2ac00000
	v_add_u32_e32 v174, s82, v184
	s_addc_u32 s61, s23, 0
	v_ashrrev_i32_e32 v175, 31, v174
	s_and_saveexec_b64 vcc, s[10:11]
	s_cbranch_execz .LBB0_665
	ds_read_b128 v[112:115], v187
	ds_read_b128 v[120:123], v187 offset:16
	s_ashr_i32 s29, s28, 31
	s_waitcnt lgkmcnt(1)
	v_mov_b32_e32 v124, v112
	s_waitcnt lgkmcnt(0)
	v_mov_b32_e32 v125, v120
	v_mov_b32_e32 v126, v114
	v_mov_b32_e32 v127, v122
	v_pk_add_f32 v[124:125], v[124:125], v[126:127]
	v_mov_b32_e32 v120, v113
	v_mov_b32_e32 v122, v115
	v_add_f32_e32 v114, v124, v125
	v_pk_add_f32 v[112:113], v[120:121], v[122:123]
	s_nop 0
	v_add_f32_e32 v113, v112, v113
	v_mul_f32_e32 v112, 0x3b800000, v114
	v_fma_f32 v113, -v114, v112, v113
	v_lshlrev_b64 v[114:115], 6, v[174:175]
	v_lshl_add_u64 v[114:115], s[60:61], 0, v[114:115]
	v_max_f32_e32 v113, 0, v113
	v_lshl_add_u64 v[114:115], s[28:29], 3, v[114:115]
	global_store_dwordx2 v[114:115], v[112:113], off sc1

.LBB0_817:
	v_readlane_b32 s6, v254, 35
	s_waitcnt lgkmcnt(0)
	s_add_u32 s6, s26, s6
	s_addc_u32 s7, s27, 0
	s_add_u32 s45, s6, 0x100000
	s_addc_u32 s59, s7, 0
	s_lshr_b32 s6, s72, 14
	s_add_i32 s60, s6, 8
	s_ashr_i32 s61, s64, 4
	s_and_b64 s[6:7], s[18:19], exec
	s_cselect_b32 s6, s60, s61
	s_lshl_b32 s60, s82, 8
	s_mul_hi_i32 s7, s6, 0x4800
	s_mulk_i32 s6, 0x4800
	s_or_b32 s69, s60, s47
	s_lshl_b64 s[18:19], s[6:7], 2
	v_or_b32_e32 v132, s69, v181
	s_add_u32 s6, s45, s18
	s_addc_u32 s7, s59, s19
	v_ashrrev_i32_e32 v133, 31, v132
	v_lshl_add_u64 v[132:133], v[132:133], 2, s[6:7]
	s_mov_b32 s6, 0x10000
	v_add_co_u32_e32 v140, vcc, s6, v132
	v_lshl_add_u64 v[144:145], v[132:133], 0, s[76:77]
	s_nop 0
	v_addc_co_u32_e32 v141, vcc, 0, v133, vcc
	global_load_dwordx4 v[132:135], v[144:145], off offset:64
	global_load_dwordx4 v[136:139], v[144:145], off offset:512
	s_nop 0
	global_load_dwordx4 v[140:143], v[140:141], off
	s_nop 0
	global_load_dwordx4 v[152:155], v[144:145], off offset:576
	v_or3_b32 v144, v185, s47, v183
	v_add_u32_e32 v144, s60, v144
	v_ashrrev_i32_e32 v145, 31, v144
	v_readlane_b32 s6, v254, 46
	v_lshl_add_u64 v[178:179], v[144:145], 2, s[56:57]
	v_readlane_b32 s7, v254, 47
	v_lshl_add_u64 v[148:149], v[178:179], 0, s[36:37]
	global_load_dwordx4 v[144:147], v[148:149], off nt
	s_nop 0
	global_load_dwordx4 v[148:151], v[148:149], off offset:512 nt
	v_lshl_add_u64 v[166:167], v[178:179], 0, s[6:7]
	v_readlane_b32 s6, v254, 50
	global_load_dwordx4 v[156:159], v[166:167], off nt
	s_nop 0
	global_load_dwordx4 v[166:169], v[166:167], off offset:512 nt
	v_readlane_b32 s7, v254, 51
	v_lshl_add_u64 v[174:175], v[178:179], 0, s[42:43]
	global_load_dwordx4 v[170:173], v[174:175], off nt
	s_nop 0
	global_load_dwordx4 v[174:177], v[174:175], off offset:512 nt
	v_lshl_add_u64 v[196:197], v[178:179], 0, s[6:7]
	v_readlane_b32 s6, v254, 54
	v_readlane_b32 s7, v254, 55
	global_load_dwordx4 v[192:195], v[196:197], off nt
	s_nop 0
	global_load_dwordx4 v[196:199], v[196:197], off offset:512 nt
	v_lshl_add_u64 v[204:205], v[178:179], 0, s[48:49]
	v_lshl_add_u64 v[208:209], v[178:179], 0, s[6:7]
	v_readlane_b32 s6, v254, 58
	global_load_dwordx4 v[200:203], v[204:205], off nt
	s_nop 0
	global_load_dwordx4 v[204:207], v[204:205], off offset:512 nt
	s_nop 0
	global_load_dwordx4 v[214:217], v[208:209], off nt
	global_load_dwordx4 v[218:221], v[208:209], off offset:512 nt
	v_lshl_add_u64 v[208:209], v[178:179], 0, s[54:55]
	v_readlane_b32 s7, v254, 59
	global_load_dwordx4 v[222:225], v[208:209], off nt
	global_load_dwordx4 v[226:229], v[208:209], off offset:512 nt
	v_lshl_add_u64 v[208:209], v[178:179], 0, s[6:7]
	global_load_dwordx4 v[230:233], v[208:209], off nt
	global_load_dwordx4 v[234:237], v[208:209], off offset:512 nt
	s_waitcnt vmcnt(15)
	ds_write_b128 v184, v[144:147]
	s_waitcnt vmcnt(13)
	ds_write_b128 v184, v[156:159] offset:1152
	ds_read_b128 v[144:147], v182
	ds_read_b128 v[238:241], v182 offset:64
	ds_write_b128 v184, v[148:151]
	s_waitcnt vmcnt(12)
	ds_write_b128 v184, v[166:169] offset:1152
	ds_read_b128 v[148:151], v182
	ds_read_b128 v[250:253], v182 offset:64
	v_pk_add_f32 v[142:143], v[142:143], 1.0 op_sel_hi:[1,0]
	v_pk_add_f32 v[140:141], v[140:141], 1.0 op_sel_hi:[1,0]
	s_waitcnt lgkmcnt(5)
	v_pk_mul_f32 v[146:147], v[146:147], s[80:81] op_sel_hi:[1,0]
	v_pk_mul_f32 v[144:145], v[144:145], s[80:81] op_sel_hi:[1,0]
	v_pk_mul_f32 v[156:157], v[142:143], 0.5 op_sel_hi:[1,0]
	v_pk_mul_f32 v[158:159], v[140:141], 0.5 op_sel_hi:[1,0]
	s_waitcnt vmcnt(11)
	ds_write_b128 v184, v[170:173]
	s_waitcnt vmcnt(9)
	ds_write_b128 v184, v[192:195] offset:1152
	v_pk_fma_f32 v[142:143], v[130:131], v[156:157], v[146:147]
	v_pk_fma_f32 v[140:141], v[128:129], v[158:159], v[144:145]
	ds_read_b128 v[128:131], v182
	ds_read_b128 v[192:195], v182 offset:64
	v_pk_add_f32 v[134:135], v[134:135], 1.0 op_sel_hi:[1,0]
	v_pk_add_f32 v[132:133], v[132:133], 1.0 op_sel_hi:[1,0]
	s_waitcnt lgkmcnt(8)
	v_pk_mul_f32 v[144:145], v[240:241], s[80:81] op_sel_hi:[1,0]
	v_pk_mul_f32 v[208:209], v[238:239], s[80:81] op_sel_hi:[1,0]
	v_pk_mul_f32 v[166:167], v[134:135], 0.5 op_sel_hi:[1,0]
	v_pk_mul_f32 v[168:169], v[132:133], 0.5 op_sel_hi:[1,0]
	v_pk_fma_f32 v[146:147], v[126:127], v[166:167], v[144:145]
	v_pk_fma_f32 v[144:145], v[124:125], v[168:169], v[208:209]
	v_pk_add_f32 v[132:133], v[138:139], 1.0 op_sel_hi:[1,0]
	v_pk_add_f32 v[134:135], v[136:137], 1.0 op_sel_hi:[1,0]
	s_waitcnt lgkmcnt(5)
	v_pk_mul_f32 v[124:125], v[150:151], s[80:81] op_sel_hi:[1,0]
	v_pk_mul_f32 v[126:127], v[148:149], s[80:81] op_sel_hi:[1,0]
	v_pk_mul_f32 v[170:171], v[132:133], 0.5 op_sel_hi:[1,0]
	v_pk_mul_f32 v[172:173], v[134:135], 0.5 op_sel_hi:[1,0]
	ds_write_b128 v184, v[174:177]
	s_waitcnt vmcnt(8)
	ds_write_b128 v184, v[196:199] offset:1152
	v_pk_fma_f32 v[150:151], v[122:123], v[170:171], v[124:125]
	v_pk_fma_f32 v[148:149], v[120:121], v[172:173], v[126:127]
	ds_read_b128 v[120:123], v182
	ds_read_b128 v[196:199], v182 offset:64
	v_pk_add_f32 v[132:133], v[154:155], 1.0 op_sel_hi:[1,0]
	v_pk_add_f32 v[134:135], v[152:153], 1.0 op_sel_hi:[1,0]
	s_waitcnt lgkmcnt(8)
	v_pk_mul_f32 v[124:125], v[252:253], s[80:81] op_sel_hi:[1,0]
	v_pk_mul_f32 v[126:127], v[250:251], s[80:81] op_sel_hi:[1,0]
	v_pk_mul_f32 v[174:175], v[132:133], 0.5 op_sel_hi:[1,0]
	v_pk_mul_f32 v[176:177], v[134:135], 0.5 op_sel_hi:[1,0]
	v_pk_fma_f32 v[154:155], v[110:111], v[174:175], v[124:125]
	v_pk_fma_f32 v[152:153], v[108:109], v[176:177], v[126:127]
	s_waitcnt lgkmcnt(5)
	v_pk_mul_f32 v[108:109], v[130:131], s[80:81] op_sel_hi:[1,0]
	v_pk_mul_f32 v[110:111], v[128:129], s[80:81] op_sel_hi:[1,0]
	v_pk_fma_f32 v[134:135], v[118:119], v[156:157], v[108:109]
	v_pk_fma_f32 v[132:133], v[116:117], v[158:159], v[110:111]
	s_waitcnt lgkmcnt(4)
	v_pk_mul_f32 v[108:109], v[194:195], s[80:81] op_sel_hi:[1,0]
	v_pk_mul_f32 v[110:111], v[192:193], s[80:81] op_sel_hi:[1,0]
	v_pk_fma_f32 v[138:139], v[114:115], v[166:167], v[108:109]
	v_pk_fma_f32 v[136:137], v[112:113], v[168:169], v[110:111]
	s_waitcnt lgkmcnt(1)
	v_pk_mul_f32 v[108:109], v[122:123], s[80:81] op_sel_hi:[1,0]
	v_pk_mul_f32 v[110:111], v[120:121], s[80:81] op_sel_hi:[1,0]
	v_pk_fma_f32 v[126:127], v[106:107], v[170:171], v[108:109]
	v_pk_fma_f32 v[124:125], v[104:105], v[172:173], v[110:111]
	s_waitcnt lgkmcnt(0)
	v_pk_mul_f32 v[104:105], v[198:199], s[80:81] op_sel_hi:[1,0]
	v_pk_mul_f32 v[106:107], v[196:197], s[80:81] op_sel_hi:[1,0]
	v_readlane_b32 s6, v254, 60
	v_pk_fma_f32 v[130:131], v[102:103], v[174:175], v[104:105]
	v_pk_fma_f32 v[128:129], v[100:101], v[176:177], v[106:107]
	v_readlane_b32 s7, v254, 61
	v_lshl_add_u64 v[104:105], v[178:179], 0, s[62:63]
	global_load_dwordx4 v[100:103], v[104:105], off nt
	s_nop 0
	global_load_dwordx4 v[104:107], v[104:105], off offset:512 nt
	v_lshl_add_u64 v[108:109], v[178:179], 0, s[6:7]
	v_readlane_b32 s6, v254, 62
	global_load_dwordx4 v[112:115], v[108:109], off nt
	global_load_dwordx4 v[192:195], v[108:109], off offset:512 nt
	v_lshl_add_u64 v[108:109], v[178:179], 0, s[96:97]
	v_readlane_b32 s7, v254, 63
	global_load_dwordx4 v[196:199], v[108:109], off nt
	global_load_dwordx4 v[238:241], v[108:109], off offset:512 nt
	v_lshl_add_u64 v[108:109], v[178:179], 0, s[6:7]
	global_load_dwordx4 v[250:253], v[108:109], off nt
	global_load_dwordx4 v[208:211], v[108:109], off offset:512 nt
	s_waitcnt vmcnt(15)
	ds_write_b128 v184, v[200:203]
	s_waitcnt vmcnt(13)
	ds_write_b128 v184, v[214:217] offset:1152
	ds_read_b128 v[108:111], v182
	ds_read_b128 v[120:123], v182 offset:64
	ds_write_b128 v184, v[204:207]
	s_waitcnt vmcnt(12)
	ds_write_b128 v184, v[218:221] offset:1152
	ds_read_b128 v[200:203], v182
	ds_read_b128 v[204:207], v182 offset:64
	s_waitcnt vmcnt(11)
	ds_write_b128 v184, v[222:225]
	s_waitcnt vmcnt(9)
	ds_write_b128 v184, v[230:233] offset:1152
	ds_read_b128 v[214:217], v182
	ds_read_b128 v[218:221], v182 offset:64
	s_waitcnt lgkmcnt(9)
	v_pk_mul_f32 v[110:111], v[110:111], s[80:81] op_sel_hi:[1,0]
	v_pk_mul_f32 v[108:109], v[108:109], s[80:81] op_sel_hi:[1,0]
	v_pk_fma_f32 v[118:119], v[98:99], v[156:157], v[110:111]
	v_pk_fma_f32 v[116:117], v[96:97], v[158:159], v[108:109]
	s_waitcnt lgkmcnt(8)
	v_pk_mul_f32 v[96:97], v[122:123], s[80:81] op_sel_hi:[1,0]
	v_pk_mul_f32 v[98:99], v[120:121], s[80:81] op_sel_hi:[1,0]
	v_pk_fma_f32 v[122:123], v[94:95], v[166:167], v[96:97]
	v_pk_fma_f32 v[120:121], v[92:93], v[168:169], v[98:99]
	s_waitcnt lgkmcnt(5)
	v_pk_mul_f32 v[92:93], v[202:203], s[80:81] op_sel_hi:[1,0]
	v_pk_mul_f32 v[94:95], v[200:201], s[80:81] op_sel_hi:[1,0]
	ds_write_b128 v184, v[226:229]
	s_waitcnt vmcnt(8)
	ds_write_b128 v184, v[234:237] offset:1152
	v_pk_fma_f32 v[98:99], v[90:91], v[170:171], v[92:93]
	v_pk_fma_f32 v[96:97], v[88:89], v[172:173], v[94:95]
	ds_read_b128 v[88:91], v182
	ds_read_b128 v[92:95], v182 offset:64
	s_waitcnt lgkmcnt(8)
	v_pk_mul_f32 v[108:109], v[206:207], s[80:81] op_sel_hi:[1,0]
	v_pk_mul_f32 v[200:201], v[204:205], s[80:81] op_sel_hi:[1,0]
	v_pk_fma_f32 v[110:111], v[74:75], v[174:175], v[108:109]
	v_pk_fma_f32 v[108:109], v[72:73], v[176:177], v[200:201]
	s_waitcnt lgkmcnt(5)
	v_pk_mul_f32 v[72:73], v[216:217], s[80:81] op_sel_hi:[1,0]
	v_pk_mul_f32 v[74:75], v[214:215], s[80:81] op_sel_hi:[1,0]
	v_pk_fma_f32 v[82:83], v[82:83], v[156:157], v[72:73]
	v_pk_fma_f32 v[80:81], v[80:81], v[158:159], v[74:75]
	s_waitcnt lgkmcnt(4)
	v_pk_mul_f32 v[72:73], v[220:221], s[80:81] op_sel_hi:[1,0]
	v_pk_mul_f32 v[74:75], v[218:219], s[80:81] op_sel_hi:[1,0]
	v_pk_fma_f32 v[86:87], v[86:87], v[166:167], v[72:73]
	v_pk_fma_f32 v[84:85], v[84:85], v[168:169], v[74:75]
	s_waitcnt lgkmcnt(1)
	v_pk_mul_f32 v[72:73], v[90:91], s[80:81] op_sel_hi:[1,0]
	v_pk_mul_f32 v[74:75], v[88:89], s[80:81] op_sel_hi:[1,0]
	v_pk_fma_f32 v[70:71], v[70:71], v[170:171], v[72:73]
	s_waitcnt lgkmcnt(0)
	v_pk_mul_f32 v[72:73], v[94:95], s[80:81] op_sel_hi:[1,0]
	v_pk_mul_f32 v[88:89], v[92:93], s[80:81] op_sel_hi:[1,0]
	v_pk_fma_f32 v[68:69], v[68:69], v[172:173], v[74:75]
	v_pk_fma_f32 v[74:75], v[66:67], v[174:175], v[72:73]
	v_pk_fma_f32 v[72:73], v[64:65], v[176:177], v[88:89]
	v_readlane_b32 s6, v255, 0
	v_lshl_add_u64 v[64:65], v[178:179], 0, s[70:71]
	v_readlane_b32 s7, v255, 1
	global_load_dwordx4 v[88:91], v[64:65], off nt
	global_load_dwordx4 v[92:95], v[64:65], off offset:512 nt
	v_lshl_add_u64 v[64:65], v[178:179], 0, s[6:7]
	v_readlane_b32 s6, v255, 2
	global_load_dwordx4 v[200:203], v[64:65], off nt
	global_load_dwordx4 v[204:207], v[64:65], off offset:512 nt
	v_lshl_add_u64 v[64:65], v[178:179], 0, s[14:15]
	v_readlane_b32 s7, v255, 3
	global_load_dwordx4 v[214:217], v[64:65], off nt
	global_load_dwordx4 v[218:221], v[64:65], off offset:512 nt
	v_lshl_add_u64 v[64:65], v[178:179], 0, s[6:7]
	global_load_dwordx4 v[222:225], v[64:65], off nt
	global_load_dwordx4 v[226:229], v[64:65], off offset:512 nt
	s_waitcnt vmcnt(15)
	ds_write_b128 v184, v[100:103]
	s_waitcnt vmcnt(13)
	ds_write_b128 v184, v[112:115] offset:1152
	ds_read_b128 v[64:67], v182
	ds_read_b128 v[100:103], v182 offset:64
	ds_write_b128 v184, v[104:107]
	s_waitcnt vmcnt(12)
	ds_write_b128 v184, v[192:195] offset:1152
	ds_read_b128 v[104:107], v182
	ds_read_b128 v[112:115], v182 offset:64
	s_waitcnt vmcnt(11)
	ds_write_b128 v184, v[196:199]
	s_waitcnt vmcnt(9)
	ds_write_b128 v184, v[250:253] offset:1152
	ds_read_b128 v[192:195], v182
	ds_read_b128 v[196:199], v182 offset:64
	s_waitcnt lgkmcnt(9)
	v_pk_mul_f32 v[64:65], v[64:65], s[80:81] op_sel_hi:[1,0]
	v_pk_mul_f32 v[66:67], v[66:67], s[80:81] op_sel_hi:[1,0]
	v_pk_fma_f32 v[60:61], v[60:61], v[158:159], v[64:65]
	s_waitcnt lgkmcnt(8)
	v_pk_mul_f32 v[64:65], v[102:103], s[80:81] op_sel_hi:[1,0]
	v_pk_mul_f32 v[100:101], v[100:101], s[80:81] op_sel_hi:[1,0]
	v_pk_fma_f32 v[62:63], v[62:63], v[156:157], v[66:67]
	v_pk_fma_f32 v[66:67], v[58:59], v[166:167], v[64:65]
	v_pk_fma_f32 v[64:65], v[56:57], v[168:169], v[100:101]
	ds_write_b128 v184, v[238:241]
	s_waitcnt vmcnt(8)
	ds_write_b128 v184, v[208:211] offset:1152
	s_waitcnt lgkmcnt(7)
	v_pk_mul_f32 v[56:57], v[106:107], s[80:81] op_sel_hi:[1,0]
	v_pk_mul_f32 v[58:59], v[104:105], s[80:81] op_sel_hi:[1,0]
	ds_read_b128 v[100:103], v182
	ds_read_b128 v[104:107], v182 offset:64
	v_pk_fma_f32 v[54:55], v[54:55], v[170:171], v[56:57]
	s_waitcnt lgkmcnt(8)
	v_pk_mul_f32 v[56:57], v[114:115], s[80:81] op_sel_hi:[1,0]
	v_pk_mul_f32 v[112:113], v[112:113], s[80:81] op_sel_hi:[1,0]
	v_pk_fma_f32 v[52:53], v[52:53], v[172:173], v[58:59]
	v_pk_fma_f32 v[58:59], v[42:43], v[174:175], v[56:57]
	v_pk_fma_f32 v[56:57], v[40:41], v[176:177], v[112:113]
	s_waitcnt lgkmcnt(5)
	v_pk_mul_f32 v[40:41], v[194:195], s[80:81] op_sel_hi:[1,0]
	v_pk_mul_f32 v[42:43], v[192:193], s[80:81] op_sel_hi:[1,0]
	v_pk_fma_f32 v[46:47], v[46:47], v[156:157], v[40:41]
	v_pk_fma_f32 v[44:45], v[44:45], v[158:159], v[42:43]
	s_waitcnt lgkmcnt(4)
	v_pk_mul_f32 v[40:41], v[198:199], s[80:81] op_sel_hi:[1,0]
	v_pk_mul_f32 v[42:43], v[196:197], s[80:81] op_sel_hi:[1,0]
	v_pk_fma_f32 v[50:51], v[50:51], v[166:167], v[40:41]
	v_pk_fma_f32 v[48:49], v[48:49], v[168:169], v[42:43]
	s_waitcnt lgkmcnt(1)
	v_pk_mul_f32 v[40:41], v[102:103], s[80:81] op_sel_hi:[1,0]
	v_pk_mul_f32 v[42:43], v[100:101], s[80:81] op_sel_hi:[1,0]
	v_pk_fma_f32 v[38:39], v[38:39], v[170:171], v[40:41]
	s_waitcnt lgkmcnt(0)
	v_pk_mul_f32 v[40:41], v[106:107], s[80:81] op_sel_hi:[1,0]
	v_pk_mul_f32 v[100:101], v[104:105], s[80:81] op_sel_hi:[1,0]
	v_pk_fma_f32 v[36:37], v[36:37], v[172:173], v[42:43]
	v_pk_fma_f32 v[42:43], v[34:35], v[174:175], v[40:41]
	v_pk_fma_f32 v[40:41], v[32:33], v[176:177], v[100:101]
	s_nop 0
	s_waitcnt vmcnt(7)
	ds_write_b128 v184, v[88:91]
	s_waitcnt vmcnt(5)
	ds_write_b128 v184, v[200:203] offset:1152
	ds_read_b128 v[32:35], v182
	ds_read_b128 v[88:91], v182 offset:64
	ds_write_b128 v184, v[92:95]
	s_waitcnt vmcnt(4)
	ds_write_b128 v184, v[204:207] offset:1152
	ds_read_b128 v[92:95], v182
	ds_read_b128 v[100:103], v182 offset:64
	s_waitcnt vmcnt(3)
	ds_write_b128 v184, v[214:217]
	s_waitcnt vmcnt(1)
	ds_write_b128 v184, v[222:225] offset:1152
	ds_read_b128 v[104:107], v182
	ds_read_b128 v[112:115], v182 offset:64
	s_waitcnt lgkmcnt(9)
	v_pk_mul_f32 v[32:33], v[32:33], s[80:81] op_sel_hi:[1,0]
	v_pk_mul_f32 v[34:35], v[34:35], s[80:81] op_sel_hi:[1,0]
	v_pk_fma_f32 v[28:29], v[28:29], v[158:159], v[32:33]
	s_waitcnt lgkmcnt(8)
	v_pk_mul_f32 v[32:33], v[90:91], s[80:81] op_sel_hi:[1,0]
	v_pk_mul_f32 v[88:89], v[88:89], s[80:81] op_sel_hi:[1,0]
	v_pk_fma_f32 v[30:31], v[30:31], v[156:157], v[34:35]
	v_pk_fma_f32 v[34:35], v[26:27], v[166:167], v[32:33]
	v_pk_fma_f32 v[32:33], v[24:25], v[168:169], v[88:89]
	ds_write_b128 v184, v[218:221]
	s_waitcnt vmcnt(0)
	ds_write_b128 v184, v[226:229] offset:1152
	s_waitcnt lgkmcnt(7)
	v_pk_mul_f32 v[24:25], v[94:95], s[80:81] op_sel_hi:[1,0]
	v_pk_mul_f32 v[26:27], v[92:93], s[80:81] op_sel_hi:[1,0]
	ds_read_b128 v[88:91], v182
	ds_read_b128 v[92:95], v182 offset:64
	v_pk_fma_f32 v[22:23], v[22:23], v[170:171], v[24:25]
	s_waitcnt lgkmcnt(8)
	v_pk_mul_f32 v[24:25], v[102:103], s[80:81] op_sel_hi:[1,0]
	v_pk_mul_f32 v[100:101], v[100:101], s[80:81] op_sel_hi:[1,0]
	v_pk_fma_f32 v[20:21], v[20:21], v[172:173], v[26:27]
	v_pk_fma_f32 v[26:27], v[14:15], v[174:175], v[24:25]
	v_pk_fma_f32 v[24:25], v[12:13], v[176:177], v[100:101]
	s_waitcnt lgkmcnt(5)
	v_pk_mul_f32 v[12:13], v[106:107], s[80:81] op_sel_hi:[1,0]
	v_pk_mul_f32 v[100:101], v[104:105], s[80:81] op_sel_hi:[1,0]
	v_pk_fma_f32 v[14:15], v[78:79], v[156:157], v[12:13]
	v_pk_fma_f32 v[12:13], v[76:77], v[158:159], v[100:101]
	s_waitcnt lgkmcnt(4)
	v_pk_mul_f32 v[76:77], v[114:115], s[80:81] op_sel_hi:[1,0]
	v_pk_mul_f32 v[78:79], v[112:113], s[80:81] op_sel_hi:[1,0]
	v_pk_fma_f32 v[18:19], v[18:19], v[166:167], v[76:77]
	v_pk_fma_f32 v[16:17], v[16:17], v[168:169], v[78:79]
	s_waitcnt lgkmcnt(1)
	v_pk_mul_f32 v[76:77], v[90:91], s[80:81] op_sel_hi:[1,0]
	v_pk_mul_f32 v[78:79], v[88:89], s[80:81] op_sel_hi:[1,0]
	v_pk_fma_f32 v[6:7], v[6:7], v[170:171], v[76:77]
	s_waitcnt lgkmcnt(0)
	v_pk_mul_f32 v[76:77], v[94:95], s[80:81] op_sel_hi:[1,0]
	v_pk_fma_f32 v[4:5], v[4:5], v[172:173], v[78:79]
	v_pk_mul_f32 v[78:79], v[92:93], s[80:81] op_sel_hi:[1,0]
	v_pk_fma_f32 v[10:11], v[10:11], v[174:175], v[76:77]
	v_add_f32_e32 v76, v140, v141
	v_add_f32_e32 v77, v142, v143
	v_pk_fma_f32 v[8:9], v[8:9], v[176:177], v[78:79]
	v_add_f32_e32 v76, v76, v77
	v_mul_f32_e32 v77, v141, v141
	v_mul_f32_e32 v78, v143, v143
	v_fmac_f32_e32 v77, v140, v140
	v_fmac_f32_e32 v78, v142, v142
	v_add_f32_e32 v77, v77, v78
	v_add_f32_e32 v78, v144, v145
	v_add_f32_e32 v79, v146, v147
	v_add_f32_e32 v76, 0, v76
	v_add_f32_e32 v78, v78, v79
	v_add_f32_e32 v76, v78, v76
	v_mul_f32_e32 v78, v145, v145
	v_mul_f32_e32 v79, v147, v147
	v_fmac_f32_e32 v78, v144, v144
	v_fmac_f32_e32 v79, v146, v146
	v_add_f32_e32 v78, v78, v79
	v_add_f32_e32 v77, v77, v78
	v_add_f32_e32 v78, v148, v149
	v_add_f32_e32 v79, v150, v151
	v_add_f32_e32 v78, v78, v79
	v_add_f32_e32 v76, v78, v76
	v_mul_f32_e32 v78, v149, v149
	v_mul_f32_e32 v79, v151, v151
	v_fmac_f32_e32 v78, v148, v148
	v_fmac_f32_e32 v79, v150, v150
	v_add_f32_e32 v78, v78, v79
	v_add_f32_e32 v77, v78, v77
	v_add_f32_e32 v78, v152, v153
	v_add_f32_e32 v79, v154, v155
	v_add_f32_e32 v78, v78, v79
	v_add_f32_e32 v76, v78, v76
	v_mul_f32_e32 v78, v153, v153
	v_mul_f32_e32 v79, v155, v155
	v_fmac_f32_e32 v78, v152, v152
	v_fmac_f32_e32 v79, v154, v154
	v_add_f32_e32 v78, v78, v79
	v_add_f32_e32 v77, v78, v77
	v_mov_b32_e32 v78, v76
	v_mov_b32_e32 v79, v77
	s_nop 0
	v_permlane16_swap_b32_e32 v76, v78
	v_permlane16_swap_b32_e32 v77, v79
	v_add_f32_e32 v76, v76, v78
	v_add_f32_e32 v77, v77, v79
	v_mov_b32_e32 v78, v76
	v_mov_b32_e32 v79, v77
	s_nop 0
	v_permlane32_swap_b32_e32 v76, v78
	v_permlane32_swap_b32_e32 v77, v79
	s_and_saveexec_b64 s[6:7], s[8:9]
	v_pk_add_f32 v[76:77], v[76:77], v[78:79]
	ds_write_b64 v190, v[76:77]
	s_or_b64 exec, exec, s[6:7]
	v_add_f32_e32 v76, v132, v133
	v_add_f32_e32 v77, v134, v135
	v_add_f32_e32 v76, v76, v77
	v_mul_f32_e32 v77, v133, v133
	v_mul_f32_e32 v78, v135, v135
	v_fmac_f32_e32 v77, v132, v132
	v_fmac_f32_e32 v78, v134, v134
	v_add_f32_e32 v77, v77, v78
	v_add_f32_e32 v78, v136, v137
	v_add_f32_e32 v79, v138, v139
	v_add_f32_e32 v76, 0, v76
	v_add_f32_e32 v78, v78, v79
	v_add_f32_e32 v76, v78, v76
	v_mul_f32_e32 v78, v137, v137
	v_mul_f32_e32 v79, v139, v139
	v_fmac_f32_e32 v78, v136, v136
	v_fmac_f32_e32 v79, v138, v138
	v_add_f32_e32 v78, v78, v79
	v_add_f32_e32 v77, v77, v78
	v_add_f32_e32 v78, v124, v125
	v_add_f32_e32 v79, v126, v127
	v_add_f32_e32 v78, v78, v79
	v_add_f32_e32 v76, v78, v76
	v_mul_f32_e32 v78, v125, v125
	v_mul_f32_e32 v79, v127, v127
	v_fmac_f32_e32 v78, v124, v124
	v_fmac_f32_e32 v79, v126, v126
	v_add_f32_e32 v78, v78, v79
	v_add_f32_e32 v77, v78, v77
	v_add_f32_e32 v78, v128, v129
	v_add_f32_e32 v79, v130, v131
	v_add_f32_e32 v78, v78, v79
	v_add_f32_e32 v76, v78, v76
	v_mul_f32_e32 v78, v129, v129
	v_mul_f32_e32 v79, v131, v131
	v_fmac_f32_e32 v78, v128, v128
	v_fmac_f32_e32 v79, v130, v130
	v_add_f32_e32 v78, v78, v79
	v_add_f32_e32 v77, v78, v77
	v_mov_b32_e32 v78, v76
	v_mov_b32_e32 v79, v77
	s_nop 0
	v_permlane16_swap_b32_e32 v76, v78
	v_permlane16_swap_b32_e32 v77, v79
	v_add_f32_e32 v76, v76, v78
	v_add_f32_e32 v77, v77, v79
	v_mov_b32_e32 v78, v76
	v_mov_b32_e32 v79, v77
	s_nop 0
	v_permlane32_swap_b32_e32 v76, v78
	v_permlane32_swap_b32_e32 v77, v79
	s_and_saveexec_b64 s[6:7], s[8:9]
	v_pk_add_f32 v[76:77], v[76:77], v[78:79]
	ds_write_b64 v190, v[76:77] offset:512
	s_or_b64 exec, exec, s[6:7]
	v_add_f32_e32 v76, v116, v117
	v_add_f32_e32 v77, v118, v119
	v_add_f32_e32 v76, v76, v77
	v_mul_f32_e32 v77, v117, v117
	v_mul_f32_e32 v78, v119, v119
	v_fmac_f32_e32 v77, v116, v116
	v_fmac_f32_e32 v78, v118, v118
	v_add_f32_e32 v77, v77, v78
	v_add_f32_e32 v78, v120, v121
	v_add_f32_e32 v79, v122, v123
	v_add_f32_e32 v76, 0, v76
	v_add_f32_e32 v78, v78, v79
	v_add_f32_e32 v76, v78, v76
	v_mul_f32_e32 v78, v121, v121
	v_mul_f32_e32 v79, v123, v123
	v_fmac_f32_e32 v78, v120, v120
	v_fmac_f32_e32 v79, v122, v122
	v_add_f32_e32 v78, v78, v79
	v_add_f32_e32 v77, v77, v78
	v_add_f32_e32 v78, v96, v97
	v_add_f32_e32 v79, v98, v99
	v_add_f32_e32 v78, v78, v79
	v_add_f32_e32 v76, v78, v76
	v_mul_f32_e32 v78, v97, v97
	v_mul_f32_e32 v79, v99, v99
	v_fmac_f32_e32 v78, v96, v96
	v_fmac_f32_e32 v79, v98, v98
	v_add_f32_e32 v78, v78, v79
	v_add_f32_e32 v77, v78, v77
	v_add_f32_e32 v78, v108, v109
	v_add_f32_e32 v79, v110, v111
	v_add_f32_e32 v78, v78, v79
	v_add_f32_e32 v76, v78, v76
	v_mul_f32_e32 v78, v109, v109
	v_mul_f32_e32 v79, v111, v111
	v_fmac_f32_e32 v78, v108, v108
	v_fmac_f32_e32 v79, v110, v110
	v_add_f32_e32 v78, v78, v79
	v_add_f32_e32 v77, v78, v77
	v_mov_b32_e32 v78, v76
	v_mov_b32_e32 v79, v77
	s_nop 0
	v_permlane16_swap_b32_e32 v76, v78
	v_permlane16_swap_b32_e32 v77, v79
	v_add_f32_e32 v76, v76, v78
	v_add_f32_e32 v77, v77, v79
	v_mov_b32_e32 v78, v76
	v_mov_b32_e32 v79, v77
	s_nop 0
	v_permlane32_swap_b32_e32 v76, v78
	v_permlane32_swap_b32_e32 v77, v79
	s_and_saveexec_b64 s[6:7], s[8:9]
	v_pk_add_f32 v[76:77], v[76:77], v[78:79]
	ds_write_b64 v190, v[76:77] offset:1024
	s_or_b64 exec, exec, s[6:7]
	v_add_f32_e32 v76, v80, v81
	v_add_f32_e32 v77, v82, v83
	v_add_f32_e32 v76, v76, v77
	v_mul_f32_e32 v77, v81, v81
	v_mul_f32_e32 v78, v83, v83
	v_fmac_f32_e32 v77, v80, v80
	v_fmac_f32_e32 v78, v82, v82
	v_add_f32_e32 v77, v77, v78
	v_add_f32_e32 v78, v84, v85
	v_add_f32_e32 v79, v86, v87
	v_add_f32_e32 v76, 0, v76
	v_add_f32_e32 v78, v78, v79
	v_add_f32_e32 v76, v78, v76
	v_mul_f32_e32 v78, v85, v85
	v_mul_f32_e32 v79, v87, v87
	v_fmac_f32_e32 v78, v84, v84
	v_fmac_f32_e32 v79, v86, v86
	v_add_f32_e32 v78, v78, v79
	v_add_f32_e32 v77, v77, v78
	v_add_f32_e32 v78, v68, v69
	v_add_f32_e32 v79, v70, v71
	v_add_f32_e32 v78, v78, v79
	v_add_f32_e32 v76, v78, v76
	v_mul_f32_e32 v78, v69, v69
	v_mul_f32_e32 v79, v71, v71
	v_fmac_f32_e32 v78, v68, v68
	v_fmac_f32_e32 v79, v70, v70
	v_add_f32_e32 v78, v78, v79
	v_add_f32_e32 v77, v78, v77
	v_add_f32_e32 v78, v72, v73
	v_add_f32_e32 v79, v74, v75
	v_add_f32_e32 v78, v78, v79
	v_add_f32_e32 v76, v78, v76
	v_mul_f32_e32 v78, v73, v73
	v_mul_f32_e32 v79, v75, v75
	v_fmac_f32_e32 v78, v72, v72
	v_fmac_f32_e32 v79, v74, v74
	v_add_f32_e32 v78, v78, v79
	v_add_f32_e32 v77, v78, v77
	v_mov_b32_e32 v78, v76
	v_mov_b32_e32 v79, v77
	s_nop 0
	v_permlane16_swap_b32_e32 v76, v78
	v_permlane16_swap_b32_e32 v77, v79
	v_add_f32_e32 v76, v76, v78
	v_add_f32_e32 v77, v77, v79
	v_mov_b32_e32 v78, v76
	v_mov_b32_e32 v79, v77
	s_nop 0
	v_permlane32_swap_b32_e32 v76, v78
	v_permlane32_swap_b32_e32 v77, v79
	s_and_saveexec_b64 s[6:7], s[8:9]
	v_pk_add_f32 v[76:77], v[76:77], v[78:79]
	ds_write_b64 v190, v[76:77] offset:1536
	s_or_b64 exec, exec, s[6:7]
	v_add_f32_e32 v76, v60, v61
	v_add_f32_e32 v77, v62, v63
	v_add_f32_e32 v76, v76, v77
	v_mul_f32_e32 v77, v61, v61
	v_mul_f32_e32 v78, v63, v63
	v_fmac_f32_e32 v77, v60, v60
	v_fmac_f32_e32 v78, v62, v62
	v_add_f32_e32 v77, v77, v78
	v_add_f32_e32 v78, v64, v65
	v_add_f32_e32 v79, v66, v67
	v_add_f32_e32 v76, 0, v76
	v_add_f32_e32 v78, v78, v79
	v_add_f32_e32 v76, v78, v76
	v_mul_f32_e32 v78, v65, v65
	v_mul_f32_e32 v79, v67, v67
	v_fmac_f32_e32 v78, v64, v64
	v_fmac_f32_e32 v79, v66, v66
	v_add_f32_e32 v78, v78, v79
	v_add_f32_e32 v77, v77, v78
	v_add_f32_e32 v78, v52, v53
	v_add_f32_e32 v79, v54, v55
	v_add_f32_e32 v78, v78, v79
	v_add_f32_e32 v76, v78, v76
	v_mul_f32_e32 v78, v53, v53
	v_mul_f32_e32 v79, v55, v55
	v_fmac_f32_e32 v78, v52, v52
	v_fmac_f32_e32 v79, v54, v54
	v_add_f32_e32 v78, v78, v79
	v_add_f32_e32 v77, v78, v77
	v_add_f32_e32 v78, v56, v57
	v_add_f32_e32 v79, v58, v59
	v_add_f32_e32 v78, v78, v79
	v_add_f32_e32 v76, v78, v76
	v_mul_f32_e32 v78, v57, v57
	v_mul_f32_e32 v79, v59, v59
	v_fmac_f32_e32 v78, v56, v56
	v_fmac_f32_e32 v79, v58, v58
	v_add_f32_e32 v78, v78, v79
	v_add_f32_e32 v77, v78, v77
	v_mov_b32_e32 v78, v76
	v_mov_b32_e32 v79, v77
	s_nop 0
	v_permlane16_swap_b32_e32 v76, v78
	v_permlane16_swap_b32_e32 v77, v79
	v_add_f32_e32 v76, v76, v78
	v_add_f32_e32 v77, v77, v79
	v_mov_b32_e32 v78, v76
	v_mov_b32_e32 v79, v77
	s_nop 0
	v_permlane32_swap_b32_e32 v76, v78
	v_permlane32_swap_b32_e32 v77, v79
	s_and_saveexec_b64 s[6:7], s[8:9]
	v_pk_add_f32 v[76:77], v[76:77], v[78:79]
	ds_write_b64 v190, v[76:77] offset:4096
	s_or_b64 exec, exec, s[6:7]
	v_add_f32_e32 v76, v44, v45
	v_add_f32_e32 v77, v46, v47
	v_add_f32_e32 v76, v76, v77
	v_mul_f32_e32 v77, v45, v45
	v_mul_f32_e32 v78, v47, v47
	v_fmac_f32_e32 v77, v44, v44
	v_fmac_f32_e32 v78, v46, v46
	v_add_f32_e32 v77, v77, v78
	v_add_f32_e32 v78, v48, v49
	v_add_f32_e32 v79, v50, v51
	v_add_f32_e32 v76, 0, v76
	v_add_f32_e32 v78, v78, v79
	v_add_f32_e32 v76, v78, v76
	v_mul_f32_e32 v78, v49, v49
	v_mul_f32_e32 v79, v51, v51
	v_fmac_f32_e32 v78, v48, v48
	v_fmac_f32_e32 v79, v50, v50
	v_add_f32_e32 v78, v78, v79
	v_add_f32_e32 v77, v77, v78
	v_add_f32_e32 v78, v36, v37
	v_add_f32_e32 v79, v38, v39
	v_add_f32_e32 v78, v78, v79
	v_add_f32_e32 v76, v78, v76
	v_mul_f32_e32 v78, v37, v37
	v_mul_f32_e32 v79, v39, v39
	v_fmac_f32_e32 v78, v36, v36
	v_fmac_f32_e32 v79, v38, v38
	v_add_f32_e32 v78, v78, v79
	v_add_f32_e32 v77, v78, v77
	v_add_f32_e32 v78, v40, v41
	v_add_f32_e32 v79, v42, v43
	v_add_f32_e32 v78, v78, v79
	v_add_f32_e32 v76, v78, v76
	v_mul_f32_e32 v78, v41, v41
	v_mul_f32_e32 v79, v43, v43
	v_fmac_f32_e32 v78, v40, v40
	v_fmac_f32_e32 v79, v42, v42
	v_add_f32_e32 v78, v78, v79
	v_add_f32_e32 v77, v78, v77
	v_mov_b32_e32 v78, v76
	v_mov_b32_e32 v79, v77
	s_nop 0
	v_permlane16_swap_b32_e32 v76, v78
	v_permlane16_swap_b32_e32 v77, v79
	v_add_f32_e32 v76, v76, v78
	v_add_f32_e32 v77, v77, v79
	v_mov_b32_e32 v78, v76
	v_mov_b32_e32 v79, v77
	s_nop 0
	v_permlane32_swap_b32_e32 v76, v78
	v_permlane32_swap_b32_e32 v77, v79
	s_and_saveexec_b64 s[6:7], s[8:9]
	v_pk_add_f32 v[76:77], v[76:77], v[78:79]
	ds_write_b64 v190, v[76:77] offset:4608
	s_or_b64 exec, exec, s[6:7]
	v_add_f32_e32 v76, v28, v29
	v_add_f32_e32 v77, v30, v31
	v_add_f32_e32 v76, v76, v77
	v_mul_f32_e32 v77, v29, v29
	v_mul_f32_e32 v78, v31, v31
	v_fmac_f32_e32 v77, v28, v28
	v_fmac_f32_e32 v78, v30, v30
	v_add_f32_e32 v77, v77, v78
	v_add_f32_e32 v78, v32, v33
	v_add_f32_e32 v79, v34, v35
	v_add_f32_e32 v76, 0, v76
	v_add_f32_e32 v78, v78, v79
	v_add_f32_e32 v76, v78, v76
	v_mul_f32_e32 v78, v33, v33
	v_mul_f32_e32 v79, v35, v35
	v_fmac_f32_e32 v78, v32, v32
	v_fmac_f32_e32 v79, v34, v34
	v_add_f32_e32 v78, v78, v79
	v_add_f32_e32 v77, v77, v78
	v_add_f32_e32 v78, v20, v21
	v_add_f32_e32 v79, v22, v23
	v_add_f32_e32 v78, v78, v79
	v_add_f32_e32 v76, v78, v76
	v_mul_f32_e32 v78, v21, v21
	v_mul_f32_e32 v79, v23, v23
	v_fmac_f32_e32 v78, v20, v20
	v_fmac_f32_e32 v79, v22, v22
	v_add_f32_e32 v78, v78, v79
	v_add_f32_e32 v77, v78, v77
	v_add_f32_e32 v78, v24, v25
	v_add_f32_e32 v79, v26, v27
	v_add_f32_e32 v78, v78, v79
	v_add_f32_e32 v76, v78, v76
	v_mul_f32_e32 v78, v25, v25
	v_mul_f32_e32 v79, v27, v27
	v_fmac_f32_e32 v78, v24, v24
	v_fmac_f32_e32 v79, v26, v26
	v_add_f32_e32 v78, v78, v79
	v_add_f32_e32 v77, v78, v77
	v_mov_b32_e32 v78, v76
	v_mov_b32_e32 v79, v77
	s_nop 0
	v_permlane16_swap_b32_e32 v76, v78
	v_permlane16_swap_b32_e32 v77, v79
	v_add_f32_e32 v76, v76, v78
	v_add_f32_e32 v77, v77, v79
	v_mov_b32_e32 v78, v76
	v_mov_b32_e32 v79, v77
	s_nop 0
	v_permlane32_swap_b32_e32 v76, v78
	v_permlane32_swap_b32_e32 v77, v79
	s_and_saveexec_b64 s[6:7], s[8:9]
	v_pk_add_f32 v[76:77], v[76:77], v[78:79]
	ds_write_b64 v190, v[76:77] offset:5120
	s_or_b64 exec, exec, s[6:7]
	v_add_f32_e32 v76, v12, v13
	v_add_f32_e32 v77, v14, v15
	v_add_f32_e32 v76, v76, v77
	v_mul_f32_e32 v77, v13, v13
	v_mul_f32_e32 v78, v15, v15
	v_fmac_f32_e32 v77, v12, v12
	v_fmac_f32_e32 v78, v14, v14
	v_add_f32_e32 v77, v77, v78
	v_add_f32_e32 v78, v16, v17
	v_add_f32_e32 v79, v18, v19
	v_add_f32_e32 v76, 0, v76
	v_add_f32_e32 v78, v78, v79
	v_add_f32_e32 v76, v78, v76
	v_mul_f32_e32 v78, v17, v17
	v_mul_f32_e32 v79, v19, v19
	v_fmac_f32_e32 v78, v16, v16
	v_fmac_f32_e32 v79, v18, v18
	v_add_f32_e32 v78, v78, v79
	v_add_f32_e32 v77, v77, v78
	v_add_f32_e32 v78, v4, v5
	v_add_f32_e32 v79, v6, v7
	v_add_f32_e32 v78, v78, v79
	v_add_f32_e32 v76, v78, v76
	v_mul_f32_e32 v78, v5, v5
	v_mul_f32_e32 v79, v7, v7
	v_fmac_f32_e32 v78, v4, v4
	v_fmac_f32_e32 v79, v6, v6
	v_add_f32_e32 v78, v78, v79
	v_add_f32_e32 v77, v78, v77
	v_add_f32_e32 v78, v8, v9
	v_add_f32_e32 v79, v10, v11
	v_add_f32_e32 v78, v78, v79
	v_add_f32_e32 v76, v78, v76
	v_mul_f32_e32 v78, v9, v9
	v_mul_f32_e32 v79, v11, v11
	v_fmac_f32_e32 v78, v8, v8
	v_fmac_f32_e32 v79, v10, v10
	v_add_f32_e32 v78, v78, v79
	v_add_f32_e32 v77, v78, v77
	v_mov_b32_e32 v78, v76
	v_mov_b32_e32 v79, v77
	s_nop 0
	v_permlane16_swap_b32_e32 v76, v78
	v_permlane16_swap_b32_e32 v77, v79
	v_add_f32_e32 v76, v76, v78
	v_add_f32_e32 v77, v77, v79
	v_mov_b32_e32 v78, v76
	v_mov_b32_e32 v79, v77
	s_nop 0
	v_permlane32_swap_b32_e32 v76, v78
	v_permlane32_swap_b32_e32 v77, v79
	s_and_saveexec_b64 s[6:7], s[8:9]
	v_pk_add_f32 v[76:77], v[76:77], v[78:79]
	ds_write_b64 v190, v[76:77] offset:5632
	s_or_b64 exec, exec, s[6:7]
	s_waitcnt lgkmcnt(0)
	s_barrier
	s_add_u32 s56, s26, 0x1ac00000
	v_add_u32_e32 v156, s68, v186
	s_addc_u32 s57, s27, 0
	v_ashrrev_i32_e32 v157, 31, v156
	s_and_saveexec_b64 s[6:7], s[10:11]
	s_cbranch_execz .LBB0_835
	ds_read_b128 v[76:79], v189
	ds_read_b128 v[88:91], v189 offset:16
	s_ashr_i32 s83, s82, 31
	s_waitcnt lgkmcnt(1)
	v_mov_b32_e32 v92, v76
	s_waitcnt lgkmcnt(0)
	v_mov_b32_e32 v93, v88
	v_mov_b32_e32 v94, v78
	v_mov_b32_e32 v95, v90
	v_pk_add_f32 v[92:93], v[92:93], v[94:95]
	v_mov_b32_e32 v88, v77
	v_mov_b32_e32 v90, v79
	v_add_f32_e32 v78, v92, v93
	v_pk_add_f32 v[76:77], v[88:89], v[90:91]
	s_nop 0
	v_add_f32_e32 v77, v76, v77
	v_mul_f32_e32 v76, 0x3b800000, v78
	v_fma_f32 v77, -v78, v76, v77
	v_lshlrev_b64 v[78:79], 6, v[156:157]
	v_lshl_add_u64 v[78:79], s[56:57], 0, v[78:79]
	v_max_f32_e32 v77, 0, v77
	v_lshl_add_u64 v[78:79], s[82:83], 3, v[78:79]
	global_store_dwordx2 v[78:79], v[76:77], off sc1
